# ret_out decay section instruction selection: abs index difference via v_sad_u32 (54 sites), bf16 RNE via v_cvt_pk_bf16_f32 instead of the bit trick (54 sites)
# speedup vs baseline: 1.0070x; 1.0070x over previous
.LBB0_193:
	v_mul_f32_e32 v0, 0xbfb8aa3b, v65
	v_rndne_f32_e32 v1, v0
	v_sub_f32_e32 v2, v0, v1
	v_fma_f32 v0, v65, s70, -v0
	v_fmac_f32_e32 v0, 0xb2a5705f, v65
	v_add_f32_e32 v0, v2, v0
	v_cvt_i32_f32_e32 v1, v1
	v_exp_f32_e32 v0, v0
	v_cmp_nlt_f32_e32 vcc, s71, v65
	s_ashr_i32 s39, s38, 31
	s_lshl_b64 s[26:27], s[38:39], 14
	v_ldexp_f32 v0, v0, v1
	v_cndmask_b32_e32 v0, 0, v0, vcc
	v_cmp_ngt_f32_e32 vcc, s3, v65
	s_add_u32 s26, s58, s26
	v_ashrrev_i32_e32 v86, 3, v100
	v_cndmask_b32_e32 v2, v238, v0, vcc
	v_add_f32_e32 v3, 1.0, v2
	v_add_f32_e32 v0, -1.0, v3
	v_sub_f32_e32 v1, v0, v3
	v_add_f32_e32 v1, 1.0, v1
	v_sub_f32_e32 v0, v2, v0
	v_add_f32_e32 v4, v0, v1
	v_frexp_mant_f32_e32 v0, v3
	v_cmp_gt_f32_e32 vcc, s5, v0
	v_cvt_f64_f32_e32 v[0:1], v3
	v_frexp_exp_i32_f64_e32 v0, v[0:1]
	v_subbrev_co_u32_e32 v0, vcc, 0, v0, vcc
	v_sub_u32_e32 v1, 0, v0
	v_ldexp_f32 v3, v3, v1
	v_ldexp_f32 v1, v4, v1
	v_add_f32_e32 v4, -1.0, v3
	v_add_f32_e32 v7, 1.0, v3
	v_add_f32_e32 v5, 1.0, v4
	v_add_f32_e32 v15, -1.0, v7
	v_sub_f32_e32 v5, v3, v5
	v_sub_f32_e32 v3, v3, v15
	v_add_f32_e32 v5, v1, v5
	v_add_f32_e32 v1, v1, v3
	v_add_f32_e32 v3, v7, v1
	v_rcp_f32_e32 v15, v3
	v_add_f32_e32 v6, v4, v5
	v_sub_f32_e32 v4, v4, v6
	v_add_f32_e32 v4, v5, v4
	v_sub_f32_e32 v5, v7, v3
	v_add_f32_e32 v1, v1, v5
	v_mul_f32_e32 v5, v6, v15
	v_mul_f32_e32 v7, v3, v5
	v_fma_f32 v17, v5, v3, -v7
	v_fmac_f32_e32 v17, v5, v1
	v_add_f32_e32 v18, v7, v17
	v_sub_f32_e32 v19, v6, v18
	v_sub_f32_e32 v6, v6, v19
	v_sub_f32_e32 v7, v18, v7
	v_sub_f32_e32 v6, v6, v18
	v_add_f32_e32 v4, v4, v6
	v_sub_f32_e32 v6, v7, v17
	v_add_f32_e32 v4, v6, v4
	v_add_f32_e32 v6, v19, v4
	v_mul_f32_e32 v7, v15, v6
	v_mul_f32_e32 v17, v3, v7
	v_fma_f32 v3, v7, v3, -v17
	v_fmac_f32_e32 v3, v7, v1
	v_sub_f32_e32 v1, v19, v6
	v_add_f32_e32 v1, v4, v1
	v_add_f32_e32 v4, v17, v3
	v_sub_f32_e32 v18, v6, v4
	v_sub_f32_e32 v6, v6, v18
	v_sub_f32_e32 v17, v4, v17
	v_sub_f32_e32 v4, v6, v4
	v_add_f32_e32 v1, v1, v4
	v_sub_f32_e32 v3, v17, v3
	v_cvt_f32_i32_e32 v0, v0
	v_add_f32_e32 v1, v3, v1
	v_add_f32_e32 v3, v5, v7
	v_add_f32_e32 v1, v18, v1
	v_sub_f32_e32 v4, v3, v5
	v_mul_f32_e32 v1, v15, v1
	v_sub_f32_e32 v4, v7, v4
	v_add_f32_e32 v1, v4, v1
	v_mul_f32_e32 v7, 0x3f317218, v0
	v_add_f32_e32 v4, v3, v1
	v_fma_f32 v15, v0, s6, -v7
	v_mul_f32_e32 v5, v4, v4
	v_fmac_f32_e32 v15, 0xb102e308, v0
	v_sub_f32_e32 v0, v4, v3
	v_fmamk_f32 v6, v5, 0x3e9b6dac, v222
	v_sub_f32_e32 v0, v1, v0
	v_add_f32_e32 v1, v7, v15
	v_fmaak_f32 v6, v5, v6, 0x3f2aaada
	v_sub_f32_e32 v3, v1, v7
	v_ldexp_f32 v7, v4, 1
	v_mul_f32_e32 v4, v4, v5
	v_mul_f32_e32 v4, v4, v6
	v_add_f32_e32 v5, v7, v4
	v_sub_f32_e32 v6, v5, v7
	v_ldexp_f32 v0, v0, 1
	v_sub_f32_e32 v4, v4, v6
	v_add_f32_e32 v0, v0, v4
	v_add_f32_e32 v4, v5, v0
	v_sub_f32_e32 v5, v4, v5
	v_sub_f32_e32 v0, v0, v5
	v_add_f32_e32 v5, v1, v4
	v_sub_f32_e32 v6, v5, v1
	v_sub_f32_e32 v7, v5, v6
	v_sub_f32_e32 v3, v15, v3
	v_sub_f32_e32 v1, v1, v7
	v_sub_f32_e32 v4, v4, v6
	v_add_f32_e32 v1, v4, v1
	v_add_f32_e32 v4, v3, v0
	v_sub_f32_e32 v6, v4, v3
	v_sub_f32_e32 v7, v4, v6
	v_sub_f32_e32 v3, v3, v7
	v_sub_f32_e32 v0, v0, v6
	v_add_f32_e32 v1, v4, v1
	v_add_f32_e32 v0, v0, v3
	v_add_f32_e32 v3, v5, v1
	v_sub_f32_e32 v4, v3, v5
	v_sub_f32_e32 v1, v1, v4
	v_add_f32_e32 v0, v0, v1
	v_mul_f32_e32 v1, 0xbfb8aa3b, v63
	v_add_f32_e32 v0, v3, v0
	v_rndne_f32_e32 v3, v1
	v_sub_f32_e32 v4, v1, v3
	v_fma_f32 v1, v63, s70, -v1
	v_fmac_f32_e32 v1, 0xb2a5705f, v63
	v_add_f32_e32 v1, v4, v1
	v_exp_f32_e32 v1, v1
	v_cvt_i32_f32_e32 v3, v3
	v_cmp_neq_f32_e32 vcc, s21, v2
	s_addc_u32 s27, s59, s27
	v_ashrrev_i32_e32 v87, 31, v86
	v_cndmask_b32_e32 v0, v238, v0, vcc
	v_cmp_lt_f32_e64 vcc, |v2|, s7
	v_cvt_pk_bf16_f32 v82, v48, v49
	v_cvt_pk_bf16_f32 v83, v46, v47
	v_cvt_pk_bf16_f32 v84, v44, v45
	v_cvt_pk_bf16_f32 v85, v42, v43
	v_cvt_pk_bf16_f32 v40, v40, v41
	s_nop 1
	v_cndmask_b32_e32 v99, v0, v2, vcc
	v_ldexp_f32 v0, v1, v3
	v_cmp_nlt_f32_e32 vcc, s71, v63
	v_cvt_pk_bf16_f32 v41, v38, v39
	v_cvt_pk_bf16_f32 v42, v36, v37
	v_cvt_pk_bf16_f32 v43, v34, v31
	v_and_b32_e32 v101, 15, v100
	v_and_b32_e32 v107, 48, v100
	v_cndmask_b32_e32 v0, 0, v0, vcc
	v_cmp_ngt_f32_e32 vcc, s3, v63
	v_add_u32_e32 v98, s2, v107
	v_or_b32_e32 v116, 64, v101
	v_cndmask_b32_e32 v0, v238, v0, vcc
	v_add_f32_e32 v4, 1.0, v0
	v_add_f32_e32 v1, -1.0, v4
	v_sub_f32_e32 v2, v1, v4
	v_add_f32_e32 v2, 1.0, v2
	v_sub_f32_e32 v1, v0, v1
	v_add_f32_e32 v5, v1, v2
	v_frexp_mant_f32_e32 v1, v4
	v_cvt_f64_f32_e32 v[2:3], v4
	v_cmp_gt_f32_e32 vcc, s5, v1
	v_frexp_exp_i32_f64_e32 v1, v[2:3]
	s_lshl_b32 s88, s22, 1
	v_subbrev_co_u32_e32 v1, vcc, 0, v1, vcc
	v_sub_u32_e32 v2, 0, v1
	v_ldexp_f32 v3, v4, v2
	v_add_f32_e32 v4, -1.0, v3
	v_add_f32_e32 v6, 1.0, v3
	v_ldexp_f32 v2, v5, v2
	v_add_f32_e32 v5, 1.0, v4
	v_add_f32_e32 v7, -1.0, v6
	v_sub_f32_e32 v5, v3, v5
	v_sub_f32_e32 v3, v3, v7
	v_add_f32_e32 v5, v2, v5
	v_add_f32_e32 v2, v2, v3
	v_add_f32_e32 v17, v6, v2
	v_rcp_f32_e32 v3, v17
	v_add_f32_e32 v15, v4, v5
	v_sub_f32_e32 v4, v4, v15
	v_add_f32_e32 v18, v5, v4
	v_sub_f32_e32 v4, v6, v17
	v_add_f32_e32 v19, v2, v4
	v_mul_f32_e32 v2, v15, v3
	v_mul_f32_e32 v33, v17, v2
	v_fma_f32 v35, v2, v17, -v33
	v_fmac_f32_e32 v35, v2, v19
	v_add_f32_e32 v50, v33, v35
	v_sub_f32_e32 v54, v15, v50
	v_sub_f32_e32 v15, v15, v54
	v_sub_f32_e32 v33, v50, v33
	v_sub_f32_e32 v15, v15, v50
	v_add_f32_e32 v15, v18, v15
	v_sub_f32_e32 v18, v33, v35
	v_add_f32_e32 v15, v18, v15
	v_add_f32_e32 v33, v54, v15
	v_mul_f32_e32 v35, v3, v33
	global_load_dwordx4 v[4:7], v[12:13], off offset:1024
	global_load_dwordx4 v[50:53], v[12:13], off offset:1040
	v_mul_f32_e32 v63, v17, v35
	v_sub_f32_e32 v65, v54, v33
	global_load_dwordx4 v[54:57], v[12:13], off offset:1072
	global_load_dwordx4 v[58:61], v[12:13], off offset:1056
	v_lshlrev_b32_e32 v12, 4, v100
	v_fma_f32 v17, v35, v17, -v63
	v_and_b32_e32 v184, 0x70, v12
	v_fmac_f32_e32 v17, v35, v19
	v_lshl_add_u64 v[12:13], s[26:27], 0, v[184:185]
	v_lshlrev_b64 v[18:19], 7, v[86:87]
	v_lshl_add_u64 v[18:19], v[12:13], 0, v[18:19]
	global_load_dwordx4 v[66:69], v[18:19], off
	v_add_u32_e32 v18, 0x100, v100
	v_ashrrev_i32_e32 v88, 3, v18
	v_ashrrev_i32_e32 v89, 31, v88
	v_lshlrev_b64 v[18:19], 7, v[88:89]
	v_lshl_add_u64 v[18:19], v[12:13], 0, v[18:19]
	global_load_dwordx4 v[70:73], v[18:19], off
	v_add_u32_e32 v18, 0x200, v100
	v_ashrrev_i32_e32 v90, 3, v18
	v_ashrrev_i32_e32 v91, 31, v90
	v_lshlrev_b64 v[18:19], 7, v[90:91]
	v_lshl_add_u64 v[18:19], v[12:13], 0, v[18:19]
	global_load_dwordx4 v[74:77], v[18:19], off
	v_add_u32_e32 v18, 0x300, v100
	v_ashrrev_i32_e32 v92, 3, v18
	v_ashrrev_i32_e32 v93, 31, v92
	v_lshlrev_b64 v[18:19], 7, v[92:93]
	v_lshl_add_u64 v[12:13], v[12:13], 0, v[18:19]
	global_load_dwordx4 v[78:81], v[12:13], off
	v_cvt_pk_bf16_f32 v19, v8, v9
	v_cvt_pk_bf16_f32 v8, v10, v11
	v_add_f32_e32 v13, v63, v17
	v_cvt_pk_bf16_f32 v9, v26, v27
	v_cvt_pk_bf16_f32 v10, v28, v29
	v_cvt_pk_bf16_f32 v11, v32, v30
	ds_write_b128 v16, v[8:11] offset:18480
	v_mul_u32_u24_e32 v8, 0x1100, v62
	v_add_f32_e32 v12, v15, v65
	v_sub_f32_e32 v15, v13, v63
	v_sub_f32_e32 v63, v33, v13
	v_mul_u32_u24_e32 v9, 0x21c0, v62
	v_lshlrev_b32_e32 v10, 1, v64
	v_lshlrev_b32_e32 v8, 1, v8
	v_sub_f32_e32 v18, v33, v63
	v_add3_u32 v9, v14, v9, v10
	v_add3_u32 v8, s2, v10, v8
	v_sub_f32_e32 v13, v18, v13
	ds_write_b128 v16, v[82:85] offset:18432
	ds_write_b128 v16, v[40:43] offset:18448
	v_cvt_pk_bf16_f32 v18, v20, v21
	v_cvt_pk_bf16_f32 v20, v22, v23
	v_cvt_pk_bf16_f32 v21, v24, v25
	ds_write_b128 v16, v[18:21] offset:18464
	v_and_b32_e32 v32, 0xffffffe0, v64
	v_or_b32_e32 v105, v32, v101
	v_add_f32_e32 v33, v12, v13
	v_mad_u64_u32 v[12:13], s[26:27], v105, s4, v[98:99]
	v_sub_f32_e32 v15, v15, v17
	v_cvt_f32_i32_e32 v1, v1
	v_cmp_neq_f32_e32 vcc, s21, v0
	v_or_b32_e32 v129, 16, v101
	v_or_b32_e32 v128, 32, v101
	v_mul_f32_e32 v39, 0x3f317218, v1
	v_fma_f32 v40, v1, s6, -v39
	v_fmac_f32_e32 v40, 0xb102e308, v1
	v_or_b32_e32 v127, 48, v101
	v_or_b32_e32 v119, 0x50, v101
	v_or_b32_e32 v117, 0x60, v101
	v_or_b32_e32 v115, 0x70, v101
	s_mov_b32 s36, 0x800000
	s_waitcnt vmcnt(0)
	ds_write_b16 v9, v4 offset:36864
	ds_write_b16_d16_hi v8, v4 offset:37136
	ds_write_b16 v9, v5 offset:37408
	ds_write_b16_d16_hi v9, v5 offset:37680
	ds_write_b16 v9, v6 offset:37952
	ds_write_b16_d16_hi v9, v6 offset:38224
	ds_write_b16 v9, v7 offset:38496
	ds_write_b16_d16_hi v9, v7 offset:38768
	ds_write_b16 v9, v50 offset:39040
	ds_write_b16_d16_hi v9, v50 offset:39312
	ds_write_b16 v9, v51 offset:39584
	ds_write_b16_d16_hi v9, v51 offset:39856
	ds_write_b16 v9, v52 offset:40128
	ds_write_b16_d16_hi v9, v52 offset:40400
	ds_write_b16 v9, v53 offset:40672
	ds_write_b16_d16_hi v9, v53 offset:40944
	ds_write_b16 v9, v58 offset:41216
	ds_write_b16_d16_hi v9, v58 offset:41488
	ds_write_b16 v9, v59 offset:41760
	ds_write_b16_d16_hi v9, v59 offset:42032
	ds_write_b16 v9, v60 offset:42304
	ds_write_b16_d16_hi v9, v60 offset:42576
	ds_write_b16 v9, v61 offset:42848
	ds_write_b16_d16_hi v9, v61 offset:43120
	ds_write_b16 v9, v54 offset:43392
	ds_write_b16_d16_hi v9, v54 offset:43664
	ds_write_b16 v9, v55 offset:43936
	ds_write_b16_d16_hi v9, v55 offset:44208
	ds_write_b16 v9, v56 offset:44480
	ds_write_b16_d16_hi v9, v56 offset:44752
	ds_write_b16 v9, v57 offset:45024
	ds_write_b16_d16_hi v9, v57 offset:45296
	v_add_u32_e32 v4, s2, v184
	v_mad_u64_u32 v[6:7], s[26:27], v86, s4, v[4:5]
	v_add_f32_e32 v8, v15, v33
	v_add_f32_e32 v8, v63, v8
	v_mul_f32_e32 v3, v3, v8
	v_add_f32_e32 v33, v2, v35
	ds_write_b128 v6, v[66:69] offset:54272
	v_mad_u64_u32 v[6:7], s[26:27], v88, s4, v[4:5]
	v_sub_f32_e32 v2, v33, v2
	v_sub_f32_e32 v2, v35, v2
	v_add_f32_e32 v35, v2, v3
	ds_write_b128 v6, v[70:73] offset:54272
	v_mad_u64_u32 v[6:7], s[26:27], v90, s4, v[4:5]
	v_mad_u64_u32 v[4:5], s[26:27], v92, s4, v[4:5]
	v_add_f32_e32 v36, v33, v35
	ds_write_b128 v6, v[74:77] offset:54272
	v_mul_f32_e32 v37, v36, v36
	v_fmamk_f32 v2, v37, 0x3e9b6dac, v222
	v_fmaak_f32 v38, v37, v2, 0x3f2aaada
	v_sub_f32_e32 v1, v36, v33
	v_add_f32_e32 v33, v39, v40
	ds_write_b128 v4, v[78:81] offset:54272
	v_mul_u32_u24_e32 v4, 0x48, v101
	v_lshlrev_b32_e32 v110, 1, v4
	v_add_u32_e32 v34, v98, v110
	s_waitcnt lgkmcnt(0)
	s_barrier
	ds_read_b128 v[24:27], v12
	ds_read_b128 v[28:31], v12 offset:2304
	ds_read_b128 v[4:7], v34 offset:18432
	ds_read_b128 v[20:23], v12 offset:64
	ds_read_b128 v[16:19], v12 offset:2368
	ds_read_b128 v[12:15], v34 offset:18496
	s_waitcnt lgkmcnt(3)
	v_mfma_f32_16x16x32_bf16 v[8:11], v[24:27], v[4:7], 0
	v_sub_f32_e32 v1, v35, v1
	v_ldexp_f32 v1, v1, 1
	v_add3_u32 v107, s2, v110, v107
	v_mfma_f32_16x16x32_bf16 v[4:7], v[28:31], v[4:7], 0
	v_add_u32_e32 v110, 0x1b00, v107
	s_waitcnt lgkmcnt(0)
	v_mfma_f32_16x16x32_bf16 v[92:95], v[20:23], v[12:15], v[8:11]
	s_nop 2
	ds_read_b128 v[8:11], v34 offset:20736
	v_mfma_f32_16x16x32_bf16 v[60:63], v[16:19], v[12:15], v[4:7]
	ds_read_b128 v[12:15], v34 offset:20800
	s_waitcnt lgkmcnt(1)
	v_mfma_f32_16x16x32_bf16 v[2:5], v[24:27], v[8:11], 0
	v_mfma_f32_16x16x32_bf16 v[6:9], v[28:31], v[8:11], 0
	v_sub_f32_e32 v10, v33, v39
	s_waitcnt lgkmcnt(0)
	v_mfma_f32_16x16x32_bf16 v[88:91], v[20:23], v[12:15], v[2:5]
	s_nop 3
	ds_read_b128 v[2:5], v34 offset:23040
	v_mfma_f32_16x16x32_bf16 v[56:59], v[16:19], v[12:15], v[6:9]
	v_sub_f32_e32 v14, v40, v10
	v_mul_f32_e32 v10, v36, v37
	v_mul_f32_e32 v35, v10, v38
	ds_read_b128 v[10:13], v34 offset:23104
	s_waitcnt lgkmcnt(1)
	v_mfma_f32_16x16x32_bf16 v[6:9], v[24:27], v[2:5], 0
	v_ldexp_f32 v15, v36, 1
	v_add_f32_e32 v36, v15, v35
	v_sub_f32_e32 v15, v36, v15
	v_mfma_f32_16x16x32_bf16 v[2:5], v[28:31], v[2:5], 0
	v_sub_f32_e32 v15, v35, v15
	v_add_f32_e32 v1, v1, v15
	v_add_f32_e32 v15, v36, v1
	s_waitcnt lgkmcnt(0)
	v_mfma_f32_16x16x32_bf16 v[84:87], v[20:23], v[10:13], v[6:9]
	v_add_f32_e32 v35, v33, v15
	s_nop 1
	ds_read_b128 v[6:9], v34 offset:25344
	v_mfma_f32_16x16x32_bf16 v[52:55], v[16:19], v[10:13], v[2:5]
	ds_read_b128 v[10:13], v34 offset:25408
	s_nop 1
	v_sub_f32_e32 v2, v15, v36
	v_sub_f32_e32 v1, v1, v2
	s_waitcnt lgkmcnt(1)
	v_mfma_f32_16x16x32_bf16 v[2:5], v[24:27], v[6:9], 0
	v_sub_f32_e32 v36, v35, v33
	v_sub_f32_e32 v37, v35, v36
	v_sub_f32_e32 v33, v33, v37
	v_mfma_f32_16x16x32_bf16 v[6:9], v[28:31], v[6:9], 0
	v_sub_f32_e32 v15, v15, v36
	v_add_f32_e32 v15, v15, v33
	v_mad_u32_u24 v33, v116, s4, v98
	s_waitcnt lgkmcnt(0)
	v_mfma_f32_16x16x32_bf16 v[80:83], v[20:23], v[10:13], v[2:5]
	v_add_f32_e32 v34, v14, v1
	v_lshlrev_b32_e32 v36, 5, v100
	v_and_b32_e32 v104, 32, v36
	ds_read_b128 v[2:5], v33 offset:18432
	v_mfma_f32_16x16x32_bf16 v[48:51], v[16:19], v[10:13], v[6:9]
	v_sub_f32_e32 v10, v34, v14
	v_sub_f32_e32 v11, v34, v10
	v_sub_f32_e32 v14, v14, v11
	v_sub_f32_e32 v1, v1, v10
	ds_read_b128 v[10:13], v33 offset:18496
	s_waitcnt lgkmcnt(1)
	v_mfma_f32_16x16x32_bf16 v[6:9], v[24:27], v[2:5], 0
	v_add_f32_e32 v1, v1, v14
	v_add_f32_e32 v14, v34, v15
	v_add_f32_e32 v15, v35, v14
	s_waitcnt lgkmcnt(0)
	v_mfma_f32_16x16x32_bf16 v[76:79], v[20:23], v[10:13], v[6:9]
	v_lshlrev_b32_e32 v184, 1, v104
	s_movk_i32 s4, 0x110
	s_nop 0
	v_sub_f32_e32 v6, v15, v35
	v_mfma_f32_16x16x32_bf16 v[2:5], v[28:31], v[2:5], 0
	v_sub_f32_e32 v14, v14, v6
	ds_read_b128 v[6:9], v33 offset:20736
	v_add_f32_e32 v1, v1, v14
	v_mfma_f32_16x16x32_bf16 v[44:47], v[16:19], v[10:13], v[2:5]
	ds_read_b128 v[10:13], v33 offset:20800
	v_add_f32_e32 v1, v15, v1
	v_cndmask_b32_e32 v1, v238, v1, vcc
	s_waitcnt lgkmcnt(1)
	v_mfma_f32_16x16x32_bf16 v[2:5], v[24:27], v[6:9], 0
	v_cmp_lt_f32_e64 vcc, |v0|, s7
	s_nop 1
	v_cndmask_b32_e32 v103, v1, v0, vcc
	v_lshrrev_b32_e32 v0, 1, v100
	v_mfma_f32_16x16x32_bf16 v[6:9], v[28:31], v[6:9], 0
	v_bfi_b32 v102, 31, v0, v64
	v_add_u32_e32 v96, s20, v102
	v_ashrrev_i32_e32 v97, 31, v96
	s_waitcnt lgkmcnt(0)
	v_mfma_f32_16x16x32_bf16 v[72:75], v[20:23], v[10:13], v[2:5]
	s_nop 2
	ds_read_b128 v[0:3], v33 offset:23040
	v_lshlrev_b64 v[4:5], 12, v[96:97]
	v_mfma_f32_16x16x32_bf16 v[40:43], v[16:19], v[10:13], v[6:9]
	s_nop 2
	v_lshl_add_u64 v[8:9], s[48:49], 0, v[4:5]
	v_lshl_add_u64 v[34:35], v[8:9], 0, s[88:89]
	ds_read_b128 v[8:11], v33 offset:23104
	s_waitcnt lgkmcnt(1)
	v_mfma_f32_16x16x32_bf16 v[4:7], v[24:27], v[0:3], 0
	v_lshl_add_u64 v[34:35], v[34:35], 0, v[184:185]
	v_mfma_f32_16x16x32_bf16 v[12:15], v[28:31], v[0:3], 0
	s_waitcnt lgkmcnt(0)
	v_mfma_f32_16x16x32_bf16 v[68:71], v[20:23], v[8:11], v[4:7]
	global_load_dwordx4 v[0:3], v[34:35], off offset:1584
	s_nop 2
	global_load_dwordx4 v[4:7], v[34:35], off offset:1568
	ds_read_b128 v[64:67], v33 offset:25344
	v_mfma_f32_16x16x32_bf16 v[36:39], v[16:19], v[8:11], v[12:15]
	global_load_dwordx4 v[8:11], v[34:35], off offset:1552
	s_nop 1
	global_load_dwordx4 v[12:15], v[34:35], off offset:1536
	ds_read_b128 v[130:133], v33 offset:25408
	v_lshrrev_b32_e32 v33, 2, v100
	v_and_or_b32 v100, v33, 12, v32
	v_sub_u32_e32 v32, v100, v101
	v_sub_u32_e32 v33, 0, v32
	v_max_i32_e32 v32, v32, v33
	v_cvt_f32_u32_e32 v106, v32
	s_waitcnt lgkmcnt(1)
	v_mfma_f32_16x16x32_bf16 v[120:123], v[24:27], v[64:67], 0
	v_cmp_lt_i32_e32 vcc, v100, v101
	v_or_b32_e32 v109, 1, v100
	s_waitcnt lgkmcnt(0)
	v_mfma_f32_16x16x32_bf16 v[134:137], v[28:31], v[64:67], 0
	v_cndmask_b32_e32 v108, v99, v103, vcc
	v_mul_f32_e32 v106, v108, v106
	v_mul_f32_e32 v106, 0xbfb8aa3b, v106
	v_mfma_f32_16x16x32_bf16 v[64:67], v[20:23], v[130:133], v[120:123]
	v_sad_u32 v108, v109, v101, 0
	v_mfma_f32_16x16x32_bf16 v[32:35], v[16:19], v[130:133], v[134:137]
	v_exp_f32_e32 v130, v106
	v_cvt_f32_u32_e32 v108, v108
	v_cmp_lt_i32_e32 vcc, v109, v101
	s_barrier
	v_mul_f32_e32 v92, v130, v92
	v_bfe_u32 v106, v92, 16, 1
	v_add3_u32 v106, v92, v106, s97
	v_mul_lo_u32 v92, v100, s4
	v_add_u32_e32 v113, s2, v92
	v_cndmask_b32_e32 v92, v99, v103, vcc
	v_mul_f32_e32 v92, v92, v108
	v_mul_f32_e32 v92, 0xbfb8aa3b, v92
	v_exp_f32_e32 v108, v92
	v_lshlrev_b32_e32 v92, 1, v101
	v_add_u32_e32 v118, v113, v92
	v_mul_f32_e32 v93, v108, v93
	v_or_b32_e32 v108, 2, v100
	v_sad_u32 v111, v108, v101, 0
	v_cvt_f32_u32_e32 v111, v111
	ds_write_b16_d16_hi v118, v106
	v_bfe_u32 v106, v93, 16, 1
	v_cmp_lt_i32_e32 vcc, v108, v101
	v_add3_u32 v106, v93, v106, s97
	v_add_u32_e32 v114, 0x110, v113
	v_cndmask_b32_e32 v93, v99, v103, vcc
	v_mul_f32_e32 v93, v93, v111
	v_mul_f32_e32 v93, 0xbfb8aa3b, v93
	v_exp_f32_e32 v111, v93
	v_add_u32_e32 v93, v114, v92
	ds_write_b16_d16_hi v93, v106
	v_or_b32_e32 v106, 3, v100
	v_sad_u32 v112, v106, v101, 0
	v_cvt_f32_u32_e32 v112, v112
	v_mul_f32_e32 v94, v111, v94
	v_cmp_lt_i32_e32 vcc, v106, v101
	v_cvt_pk_bf16_f32 v94, v94, v94
	v_or_b32_e32 v123, 16, v100
	v_cndmask_b32_e32 v111, v99, v103, vcc
	v_mul_f32_e32 v111, v111, v112
	v_mul_f32_e32 v111, 0xbfb8aa3b, v111
	v_exp_f32_e32 v111, v111
	v_add_u32_e32 v112, 0x220, v113
	v_add_u32_e32 v120, v112, v92
	ds_write_b16_d16_hi v120, v94
	v_mul_f32_e32 v94, v111, v95
	v_sad_u32 v111, v100, v129, 0
	v_cvt_f32_u32_e32 v111, v111
	v_bfe_u32 v95, v94, 16, 1
	v_cmp_lt_i32_e32 vcc, v100, v129
	v_add3_u32 v95, v94, v95, s97
	v_or_b32_e32 v122, 17, v100
	v_cndmask_b32_e32 v94, v99, v103, vcc
	v_mul_f32_e32 v94, v94, v111
	v_mul_f32_e32 v94, 0xbfb8aa3b, v94
	v_exp_f32_e32 v121, v94
	v_add_u32_e32 v111, 0x330, v113
	v_add_u32_e32 v94, v111, v92
	ds_write_b16_d16_hi v94, v95
	v_mul_f32_e32 v88, v121, v88
	v_cvt_pk_bf16_f32 v88, v88, v88
	v_sad_u32 v95, v109, v129, 0
	v_cvt_f32_u32_e32 v95, v95
	v_cmp_lt_i32_e32 vcc, v109, v129
	ds_write_b16_d16_hi v118, v88 offset:32
	v_mul_f32_e32 v56, v130, v56
	v_cndmask_b32_e32 v88, v99, v103, vcc
	v_mul_f32_e32 v88, v88, v95
	v_sad_u32 v95, v108, v129, 0
	v_mul_f32_e32 v88, 0xbfb8aa3b, v88
	v_exp_f32_e32 v88, v88
	v_cvt_f32_u32_e32 v95, v95
	v_cmp_lt_i32_e32 vcc, v108, v129
	v_mul_f32_e32 v88, v88, v89
	v_or_b32_e32 v121, 18, v100
	v_cndmask_b32_e32 v89, v99, v103, vcc
	v_mul_f32_e32 v89, v89, v95
	v_mul_f32_e32 v89, 0xbfb8aa3b, v89
	v_exp_f32_e32 v89, v89
	v_cvt_pk_bf16_f32 v88, v88, v88
	ds_write_b16_d16_hi v93, v88 offset:32
	v_mul_f32_e32 v88, v89, v90
	v_cvt_pk_bf16_f32 v88, v88, v88
	v_sad_u32 v89, v106, v129, 0
	v_cvt_f32_u32_e32 v89, v89
	v_cmp_lt_i32_e32 vcc, v106, v129
	ds_write_b16_d16_hi v120, v88 offset:32
	s_nop 0
	v_cndmask_b32_e32 v88, v99, v103, vcc
	v_mul_f32_e32 v88, v88, v89
	v_sad_u32 v89, v100, v128, 0
	v_cvt_f32_u32_e32 v89, v89
	v_cmp_lt_i32_e32 vcc, v100, v128
	v_mul_f32_e32 v88, 0xbfb8aa3b, v88
	v_exp_f32_e32 v88, v88
	v_cndmask_b32_e32 v90, v99, v103, vcc
	v_mul_f32_e32 v89, v90, v89
	v_mul_f32_e32 v89, 0xbfb8aa3b, v89
	v_exp_f32_e32 v89, v89
	v_mul_f32_e32 v88, v88, v91
	v_cvt_pk_bf16_f32 v88, v88, v88
	v_mul_f32_e32 v84, v89, v84
	ds_write_b16_d16_hi v94, v88 offset:32
	v_cvt_pk_bf16_f32 v84, v84, v84
	v_sad_u32 v88, v109, v128, 0
	v_cvt_f32_u32_e32 v88, v88
	v_cmp_lt_i32_e32 vcc, v109, v128
	ds_write_b16_d16_hi v118, v84 offset:64
	s_nop 0
	v_cndmask_b32_e32 v84, v99, v103, vcc
	v_mul_f32_e32 v84, v84, v88
	v_sad_u32 v88, v108, v128, 0
	v_mul_f32_e32 v84, 0xbfb8aa3b, v84
	v_exp_f32_e32 v84, v84
	v_cvt_f32_u32_e32 v88, v88
	v_cmp_lt_i32_e32 vcc, v108, v128
	v_mul_f32_e32 v84, v84, v85
	s_nop 0
	v_cndmask_b32_e32 v85, v99, v103, vcc
	v_mul_f32_e32 v85, v85, v88
	v_mul_f32_e32 v85, 0xbfb8aa3b, v85
	v_exp_f32_e32 v85, v85
	v_cvt_pk_bf16_f32 v84, v84, v84
	ds_write_b16_d16_hi v93, v84 offset:64
	v_mul_f32_e32 v84, v85, v86
	v_cvt_pk_bf16_f32 v84, v84, v84
	v_sad_u32 v85, v106, v128, 0
	v_cvt_f32_u32_e32 v85, v85
	v_cmp_lt_i32_e32 vcc, v106, v128
	ds_write_b16_d16_hi v120, v84 offset:64
	v_add_u32_e32 v88, 0x1200, v107
	v_cndmask_b32_e32 v84, v99, v103, vcc
	v_mul_f32_e32 v84, v84, v85
	v_sad_u32 v85, v100, v127, 0
	v_cvt_f32_u32_e32 v85, v85
	v_cmp_lt_i32_e32 vcc, v100, v127
	v_mul_f32_e32 v84, 0xbfb8aa3b, v84
	v_exp_f32_e32 v84, v84
	v_cndmask_b32_e32 v86, v99, v103, vcc
	v_mul_f32_e32 v85, v86, v85
	v_mul_f32_e32 v85, 0xbfb8aa3b, v85
	v_exp_f32_e32 v85, v85
	v_mul_f32_e32 v84, v84, v87
	v_cvt_pk_bf16_f32 v84, v84, v84
	v_mul_f32_e32 v80, v85, v80
	ds_write_b16_d16_hi v94, v84 offset:64
	v_cvt_pk_bf16_f32 v80, v80, v80
	v_sad_u32 v84, v109, v127, 0
	v_cvt_f32_u32_e32 v84, v84
	v_cmp_lt_i32_e32 vcc, v109, v127
	ds_write_b16_d16_hi v118, v80 offset:96
	s_nop 0
	v_cndmask_b32_e32 v80, v99, v103, vcc
	v_mul_f32_e32 v80, v80, v84
	v_sad_u32 v84, v108, v127, 0
	v_mul_f32_e32 v80, 0xbfb8aa3b, v80
	v_exp_f32_e32 v80, v80
	v_cvt_f32_u32_e32 v84, v84
	v_cmp_lt_i32_e32 vcc, v108, v127
	v_mul_f32_e32 v80, v80, v81
	s_nop 0
	v_cndmask_b32_e32 v81, v99, v103, vcc
	v_mul_f32_e32 v81, v81, v84
	v_mul_f32_e32 v81, 0xbfb8aa3b, v81
	v_exp_f32_e32 v81, v81
	v_cvt_pk_bf16_f32 v80, v80, v80
	ds_write_b16_d16_hi v93, v80 offset:96
	v_mul_f32_e32 v80, v81, v82
	v_cvt_pk_bf16_f32 v80, v80, v80
	v_sad_u32 v81, v106, v127, 0
	v_cvt_f32_u32_e32 v81, v81
	v_cmp_lt_i32_e32 vcc, v106, v127
	ds_write_b16_d16_hi v120, v80 offset:96
	s_nop 0
	v_cndmask_b32_e32 v80, v99, v103, vcc
	v_mul_f32_e32 v80, v80, v81
	v_sad_u32 v81, v100, v116, 0
	v_cvt_f32_u32_e32 v81, v81
	v_cmp_lt_i32_e32 vcc, v100, v116
	v_mul_f32_e32 v80, 0xbfb8aa3b, v80
	v_exp_f32_e32 v80, v80
	v_cndmask_b32_e32 v82, v99, v103, vcc
	v_mul_f32_e32 v81, v82, v81
	v_mul_f32_e32 v81, 0xbfb8aa3b, v81
	v_exp_f32_e32 v81, v81
	v_mul_f32_e32 v80, v80, v83
	v_cvt_pk_bf16_f32 v80, v80, v80
	v_mul_f32_e32 v76, v81, v76
	ds_write_b16_d16_hi v94, v80 offset:96
	v_cvt_pk_bf16_f32 v76, v76, v76
	v_sad_u32 v80, v109, v116, 0
	v_cvt_f32_u32_e32 v80, v80
	v_cmp_lt_i32_e32 vcc, v109, v116
	ds_write_b16_d16_hi v118, v76 offset:128
	s_nop 0
	v_cndmask_b32_e32 v76, v99, v103, vcc
	v_mul_f32_e32 v76, v76, v80
	v_sad_u32 v80, v108, v116, 0
	v_mul_f32_e32 v76, 0xbfb8aa3b, v76
	v_exp_f32_e32 v76, v76
	v_cvt_f32_u32_e32 v80, v80
	v_cmp_lt_i32_e32 vcc, v108, v116
	v_mul_f32_e32 v76, v76, v77
	s_nop 0
	v_cndmask_b32_e32 v77, v99, v103, vcc
	v_mul_f32_e32 v77, v77, v80
	v_mul_f32_e32 v77, 0xbfb8aa3b, v77
	v_exp_f32_e32 v77, v77
	v_cvt_pk_bf16_f32 v76, v76, v76
	ds_write_b16_d16_hi v93, v76 offset:128
	v_mul_f32_e32 v76, v77, v78
	v_cvt_pk_bf16_f32 v76, v76, v76
	v_sad_u32 v77, v106, v116, 0
	v_cvt_f32_u32_e32 v77, v77
	v_cmp_lt_i32_e32 vcc, v106, v116
	ds_write_b16_d16_hi v120, v76 offset:128
	s_nop 0
	v_cndmask_b32_e32 v76, v99, v103, vcc
	v_mul_f32_e32 v76, v76, v77
	v_sad_u32 v77, v100, v119, 0
	v_cvt_f32_u32_e32 v77, v77
	v_cmp_lt_i32_e32 vcc, v100, v119
	v_mul_f32_e32 v76, 0xbfb8aa3b, v76
	v_exp_f32_e32 v76, v76
	v_cndmask_b32_e32 v78, v99, v103, vcc
	v_mul_f32_e32 v77, v78, v77
	v_mul_f32_e32 v77, 0xbfb8aa3b, v77
	v_exp_f32_e32 v77, v77
	v_mul_f32_e32 v76, v76, v79
	v_cvt_pk_bf16_f32 v76, v76, v76
	v_mul_f32_e32 v72, v77, v72
	ds_write_b16_d16_hi v94, v76 offset:128
	v_cvt_pk_bf16_f32 v72, v72, v72
	v_sad_u32 v76, v109, v119, 0
	v_cvt_f32_u32_e32 v76, v76
	v_cmp_lt_i32_e32 vcc, v109, v119
	ds_write_b16_d16_hi v118, v72 offset:160
	s_nop 0
	v_cndmask_b32_e32 v72, v99, v103, vcc
	v_mul_f32_e32 v72, v72, v76
	v_sad_u32 v76, v108, v119, 0
	v_mul_f32_e32 v72, 0xbfb8aa3b, v72
	v_exp_f32_e32 v72, v72
	v_cvt_f32_u32_e32 v76, v76
	v_cmp_lt_i32_e32 vcc, v108, v119
	v_mul_f32_e32 v72, v72, v73
	s_nop 0
	v_cndmask_b32_e32 v73, v99, v103, vcc
	v_mul_f32_e32 v73, v73, v76
	v_mul_f32_e32 v73, 0xbfb8aa3b, v73
	v_exp_f32_e32 v73, v73
	v_cvt_pk_bf16_f32 v72, v72, v72
	ds_write_b16_d16_hi v93, v72 offset:160
	v_mul_f32_e32 v72, v73, v74
	v_cvt_pk_bf16_f32 v72, v72, v72
	v_sad_u32 v73, v106, v119, 0
	v_cvt_f32_u32_e32 v73, v73
	v_cmp_lt_i32_e32 vcc, v106, v119
	ds_write_b16_d16_hi v120, v72 offset:160
	s_nop 0
	v_cndmask_b32_e32 v72, v99, v103, vcc
	v_mul_f32_e32 v72, v72, v73
	v_sad_u32 v73, v100, v117, 0
	v_cvt_f32_u32_e32 v73, v73
	v_cmp_lt_i32_e32 vcc, v100, v117
	v_mul_f32_e32 v72, 0xbfb8aa3b, v72
	v_exp_f32_e32 v72, v72
	v_cndmask_b32_e32 v74, v99, v103, vcc
	v_mul_f32_e32 v73, v74, v73
	v_mul_f32_e32 v73, 0xbfb8aa3b, v73
	v_exp_f32_e32 v73, v73
	v_mul_f32_e32 v72, v72, v75
	v_cvt_pk_bf16_f32 v72, v72, v72
	v_mul_f32_e32 v68, v73, v68
	ds_write_b16_d16_hi v94, v72 offset:160
	v_cvt_pk_bf16_f32 v68, v68, v68
	v_sad_u32 v72, v109, v117, 0
	v_cvt_f32_u32_e32 v72, v72
	v_cmp_lt_i32_e32 vcc, v109, v117
	ds_write_b16_d16_hi v118, v68 offset:192
	s_nop 0
	v_cndmask_b32_e32 v68, v99, v103, vcc
	v_mul_f32_e32 v68, v68, v72
	v_sad_u32 v72, v108, v117, 0
	v_mul_f32_e32 v68, 0xbfb8aa3b, v68
	v_exp_f32_e32 v68, v68
	v_cvt_f32_u32_e32 v72, v72
	v_cmp_lt_i32_e32 vcc, v108, v117
	v_mul_f32_e32 v68, v68, v69
	s_nop 0
	v_cndmask_b32_e32 v69, v99, v103, vcc
	v_mul_f32_e32 v69, v69, v72
	v_mul_f32_e32 v69, 0xbfb8aa3b, v69
	v_exp_f32_e32 v69, v69
	v_cvt_pk_bf16_f32 v68, v68, v68
	ds_write_b16_d16_hi v93, v68 offset:192
	v_mul_f32_e32 v68, v69, v70
	v_cvt_pk_bf16_f32 v68, v68, v68
	v_sad_u32 v69, v106, v117, 0
	v_cvt_f32_u32_e32 v69, v69
	v_cmp_lt_i32_e32 vcc, v106, v117
	ds_write_b16_d16_hi v120, v68 offset:192
	s_nop 0
	v_cndmask_b32_e32 v68, v99, v103, vcc
	v_mul_f32_e32 v68, v68, v69
	v_sad_u32 v69, v100, v115, 0
	v_cvt_f32_u32_e32 v69, v69
	v_cmp_lt_i32_e32 vcc, v100, v115
	v_mul_f32_e32 v68, 0xbfb8aa3b, v68
	v_exp_f32_e32 v68, v68
	v_cndmask_b32_e32 v70, v99, v103, vcc
	v_mul_f32_e32 v69, v70, v69
	v_mul_f32_e32 v69, 0xbfb8aa3b, v69
	v_exp_f32_e32 v69, v69
	v_mul_f32_e32 v68, v68, v71
	v_cvt_pk_bf16_f32 v68, v68, v68
	v_mul_f32_e32 v64, v69, v64
	ds_write_b16_d16_hi v94, v68 offset:192
	v_cvt_pk_bf16_f32 v64, v64, v64
	v_sad_u32 v68, v109, v115, 0
	v_cvt_f32_u32_e32 v68, v68
	v_cmp_lt_i32_e32 vcc, v109, v115
	ds_write_b16_d16_hi v118, v64 offset:224
	v_or_b32_e32 v118, 19, v100
	v_cndmask_b32_e32 v64, v99, v103, vcc
	v_mul_f32_e32 v64, v64, v68
	v_sad_u32 v68, v108, v115, 0
	v_mul_f32_e32 v64, 0xbfb8aa3b, v64
	v_exp_f32_e32 v64, v64
	v_cvt_f32_u32_e32 v68, v68
	v_cmp_lt_i32_e32 vcc, v108, v115
	v_mul_f32_e32 v64, v64, v65
	s_nop 0
	v_cndmask_b32_e32 v65, v99, v103, vcc
	v_mul_f32_e32 v65, v65, v68
	v_mul_f32_e32 v65, 0xbfb8aa3b, v65
	v_exp_f32_e32 v65, v65
	v_cvt_pk_bf16_f32 v64, v64, v64
	ds_write_b16_d16_hi v93, v64 offset:224
	v_mul_f32_e32 v64, v65, v66
	v_cvt_pk_bf16_f32 v64, v64, v64
	v_sad_u32 v65, v106, v115, 0
	v_cvt_f32_u32_e32 v65, v65
	v_cmp_lt_i32_e32 vcc, v106, v115
	ds_write_b16_d16_hi v120, v64 offset:224
	v_add_u32_e32 v68, 0x900, v107
	v_cndmask_b32_e32 v64, v99, v103, vcc
	v_mul_f32_e32 v64, v64, v65
	v_sad_u32 v65, v123, v101, 0
	v_cvt_f32_u32_e32 v65, v65
	v_cmp_lt_i32_e32 vcc, v123, v101
	v_mul_f32_e32 v64, 0xbfb8aa3b, v64
	v_exp_f32_e32 v64, v64
	v_cndmask_b32_e32 v66, v99, v103, vcc
	v_mul_f32_e32 v65, v66, v65
	v_mul_f32_e32 v65, 0xbfb8aa3b, v65
	v_exp_f32_e32 v65, v65
	v_mul_f32_e32 v64, v64, v67
	v_cvt_pk_bf16_f32 v64, v64, v64
	v_mul_f32_e32 v60, v65, v60
	ds_write_b16_d16_hi v94, v64 offset:224
	v_bfe_u32 v64, v60, 16, 1
	v_add3_u32 v64, v60, v64, s97
	v_sad_u32 v60, v122, v101, 0
	v_cvt_f32_u32_e32 v60, v60
	v_cmp_lt_i32_e32 vcc, v122, v101
	v_mul_lo_u32 v65, v123, s4
	v_add_u32_e32 v126, s2, v65
	v_cndmask_b32_e32 v66, v99, v103, vcc
	v_mul_f32_e32 v60, v66, v60
	v_mul_f32_e32 v60, 0xbfb8aa3b, v60
	v_exp_f32_e32 v66, v60
	v_sub_u32_e32 v65, v121, v101
	v_add_u32_e32 v60, v126, v92
	ds_write_b16_d16_hi v60, v64
	v_mul_f32_e32 v61, v66, v61
	v_sub_u32_e32 v66, 0, v65
	v_max_i32_e32 v65, v65, v66
	v_cvt_f32_u32_e32 v65, v65
	v_cmp_lt_i32_e32 vcc, v121, v101
	v_cvt_pk_bf16_f32 v61, v61, v61
	v_add_u32_e32 v125, 0x110, v126
	v_cndmask_b32_e32 v64, v99, v103, vcc
	v_mul_f32_e32 v64, v64, v65
	v_mul_f32_e32 v64, 0xbfb8aa3b, v64
	v_exp_f32_e32 v65, v64
	v_add_u32_e32 v64, v125, v92
	ds_write_b16_d16_hi v64, v61
	v_cmp_lt_i32_e32 vcc, v118, v101
	v_mul_f32_e32 v61, v65, v62
	v_sad_u32 v65, v118, v101, 0
	v_cvt_f32_u32_e32 v65, v65
	v_bfe_u32 v62, v61, 16, 1
	v_add3_u32 v62, v61, v62, s97
	v_cndmask_b32_e32 v61, v99, v103, vcc
	v_mul_f32_e32 v61, v61, v65
	v_mul_f32_e32 v61, 0xbfb8aa3b, v61
	v_exp_f32_e32 v65, v61
	v_add_u32_e32 v124, 0x220, v126
	v_add_u32_e32 v61, v124, v92
	ds_write_b16_d16_hi v61, v62
	v_mul_f32_e32 v62, v65, v63
	v_bfe_u32 v63, v62, 16, 1
	v_add_u32_e32 v120, 0x330, v126
	v_add3_u32 v63, v62, v63, s97
	v_add_u32_e32 v62, v120, v92
	ds_write_b16_d16_hi v62, v63
	v_sad_u32 v63, v122, v129, 0
	v_cvt_f32_u32_e32 v63, v63
	v_cmp_lt_i32_e32 vcc, v122, v129
	s_nop 1
	v_cndmask_b32_e32 v65, v99, v103, vcc
	v_mul_f32_e32 v63, v65, v63
	v_mul_f32_e32 v63, 0xbfb8aa3b, v63
	v_exp_f32_e32 v63, v63
	v_bfe_u32 v65, v56, 16, 1
	v_add3_u32 v56, v56, v65, s97
	ds_write_b16_d16_hi v60, v56 offset:32
	v_mul_f32_e32 v56, v63, v57
	v_cvt_pk_bf16_f32 v56, v56, v56
	v_sad_u32 v57, v121, v129, 0
	v_cvt_f32_u32_e32 v57, v57
	v_cmp_lt_i32_e32 vcc, v121, v129
	ds_write_b16_d16_hi v64, v56 offset:32
	s_nop 0
	v_cndmask_b32_e32 v56, v99, v103, vcc
	v_mul_f32_e32 v56, v56, v57
	v_sub_u32_e32 v57, v118, v129
	v_mul_f32_e32 v56, 0xbfb8aa3b, v56
	v_sub_u32_e32 v63, 0, v57
	v_exp_f32_e32 v56, v56
	v_max_i32_e32 v57, v57, v63
	v_cvt_f32_u32_e32 v57, v57
	v_cmp_lt_i32_e32 vcc, v118, v129
	v_mul_f32_e32 v56, v56, v58
	s_nop 0
	v_cndmask_b32_e32 v58, v99, v103, vcc
	v_mul_f32_e32 v57, v58, v57
	v_mul_f32_e32 v57, 0xbfb8aa3b, v57
	v_exp_f32_e32 v57, v57
	v_cvt_pk_bf16_f32 v56, v56, v56
	ds_write_b16_d16_hi v61, v56 offset:32
	v_mul_f32_e32 v56, v57, v59
	v_cvt_pk_bf16_f32 v56, v56, v56
	v_sad_u32 v57, v123, v128, 0
	v_cvt_f32_u32_e32 v57, v57
	v_cmp_lt_i32_e32 vcc, v123, v128
	ds_write_b16_d16_hi v62, v56 offset:32
	s_nop 0
	v_cndmask_b32_e32 v56, v99, v103, vcc
	v_mul_f32_e32 v56, v56, v57
	v_sub_u32_e32 v57, v122, v128
	v_mul_f32_e32 v56, 0xbfb8aa3b, v56
	v_sub_u32_e32 v58, 0, v57
	v_exp_f32_e32 v56, v56
	v_max_i32_e32 v57, v57, v58
	v_cvt_f32_u32_e32 v57, v57
	v_cmp_lt_i32_e32 vcc, v122, v128
	v_mul_f32_e32 v52, v56, v52
	s_nop 0
	v_cndmask_b32_e32 v56, v99, v103, vcc
	v_mul_f32_e32 v56, v56, v57
	v_mul_f32_e32 v56, 0xbfb8aa3b, v56
	v_exp_f32_e32 v56, v56
	v_bfe_u32 v57, v52, 16, 1
	v_add3_u32 v52, v52, v57, s97
	ds_write_b16_d16_hi v60, v52 offset:64
	v_mul_f32_e32 v52, v56, v53
	v_cvt_pk_bf16_f32 v52, v52, v52
	v_sad_u32 v53, v121, v128, 0
	v_cvt_f32_u32_e32 v53, v53
	v_cmp_lt_i32_e32 vcc, v121, v128
	ds_write_b16_d16_hi v64, v52 offset:64
	s_nop 0
	v_cndmask_b32_e32 v52, v99, v103, vcc
	v_mul_f32_e32 v52, v52, v53
	v_sub_u32_e32 v53, v118, v128
	v_mul_f32_e32 v52, 0xbfb8aa3b, v52
	v_sub_u32_e32 v56, 0, v53
	v_exp_f32_e32 v52, v52
	v_max_i32_e32 v53, v53, v56
	v_cvt_f32_u32_e32 v53, v53
	v_cmp_lt_i32_e32 vcc, v118, v128
	v_mul_f32_e32 v52, v52, v54
	s_nop 0
	v_cndmask_b32_e32 v54, v99, v103, vcc
	v_mul_f32_e32 v53, v54, v53
	v_mul_f32_e32 v53, 0xbfb8aa3b, v53
	v_exp_f32_e32 v53, v53
	v_cvt_pk_bf16_f32 v52, v52, v52
	ds_write_b16_d16_hi v61, v52 offset:64
	v_mul_f32_e32 v52, v53, v55
	v_cvt_pk_bf16_f32 v52, v52, v52
	v_sad_u32 v53, v123, v127, 0
	v_cvt_f32_u32_e32 v53, v53
	v_cmp_lt_i32_e32 vcc, v123, v127
	ds_write_b16_d16_hi v62, v52 offset:64
	s_nop 0
	v_cndmask_b32_e32 v52, v99, v103, vcc
	v_mul_f32_e32 v52, v52, v53
	v_sad_u32 v53, v122, v127, 0
	v_mul_f32_e32 v52, 0xbfb8aa3b, v52
	v_exp_f32_e32 v52, v52
	v_cvt_f32_u32_e32 v53, v53
	v_cmp_lt_i32_e32 vcc, v122, v127
	v_mul_f32_e32 v48, v52, v48
	s_nop 0
	v_cndmask_b32_e32 v52, v99, v103, vcc
	v_mul_f32_e32 v52, v52, v53
	v_mul_f32_e32 v52, 0xbfb8aa3b, v52
	v_exp_f32_e32 v52, v52
	v_cvt_pk_bf16_f32 v48, v48, v48
	ds_write_b16_d16_hi v60, v48 offset:96
	v_mul_f32_e32 v48, v52, v49
	v_cvt_pk_bf16_f32 v48, v48, v48
	v_sad_u32 v49, v121, v127, 0
	v_cvt_f32_u32_e32 v49, v49
	v_cmp_lt_i32_e32 vcc, v121, v127
	ds_write_b16_d16_hi v64, v48 offset:96
	s_nop 0
	v_cndmask_b32_e32 v48, v99, v103, vcc
	v_mul_f32_e32 v48, v48, v49
	v_sad_u32 v49, v118, v127, 0
	v_mul_f32_e32 v48, 0xbfb8aa3b, v48
	v_exp_f32_e32 v48, v48
	v_cvt_f32_u32_e32 v49, v49
	v_cmp_lt_i32_e32 vcc, v118, v127
	v_mul_f32_e32 v48, v48, v50
	s_nop 0
	v_cndmask_b32_e32 v50, v99, v103, vcc
	v_mul_f32_e32 v49, v50, v49
	v_mul_f32_e32 v49, 0xbfb8aa3b, v49
	v_exp_f32_e32 v49, v49
	v_cvt_pk_bf16_f32 v48, v48, v48
	ds_write_b16_d16_hi v61, v48 offset:96
	v_mul_f32_e32 v48, v49, v51
	v_cvt_pk_bf16_f32 v48, v48, v48
	v_sad_u32 v49, v123, v116, 0
	v_cvt_f32_u32_e32 v49, v49
	v_cmp_lt_i32_e32 vcc, v123, v116
	ds_write_b16_d16_hi v62, v48 offset:96
	s_nop 0
	v_cndmask_b32_e32 v48, v99, v103, vcc
	v_mul_f32_e32 v48, v48, v49
	v_sad_u32 v49, v122, v116, 0
	v_mul_f32_e32 v48, 0xbfb8aa3b, v48
	v_exp_f32_e32 v48, v48
	v_cvt_f32_u32_e32 v49, v49
	v_cmp_lt_i32_e32 vcc, v122, v116
	v_mul_f32_e32 v44, v48, v44
	s_nop 0
	v_cndmask_b32_e32 v48, v99, v103, vcc
	v_mul_f32_e32 v48, v48, v49
	v_mul_f32_e32 v48, 0xbfb8aa3b, v48
	v_exp_f32_e32 v48, v48
	v_cvt_pk_bf16_f32 v44, v44, v44
	ds_write_b16_d16_hi v60, v44 offset:128
	v_mul_f32_e32 v44, v48, v45
	v_cvt_pk_bf16_f32 v44, v44, v44
	v_sad_u32 v45, v121, v116, 0
	v_cvt_f32_u32_e32 v45, v45
	v_cmp_lt_i32_e32 vcc, v121, v116
	ds_write_b16_d16_hi v64, v44 offset:128
	s_nop 0
	v_cndmask_b32_e32 v44, v99, v103, vcc
	v_mul_f32_e32 v44, v44, v45
	v_sad_u32 v45, v118, v116, 0
	v_mul_f32_e32 v44, 0xbfb8aa3b, v44
	v_exp_f32_e32 v44, v44
	v_cvt_f32_u32_e32 v45, v45
	v_cmp_lt_i32_e32 vcc, v118, v116
	v_mul_f32_e32 v44, v44, v46
	s_nop 0
	v_cndmask_b32_e32 v46, v99, v103, vcc
	v_mul_f32_e32 v45, v46, v45
	v_mul_f32_e32 v45, 0xbfb8aa3b, v45
	v_exp_f32_e32 v45, v45
	v_cvt_pk_bf16_f32 v44, v44, v44
	ds_write_b16_d16_hi v61, v44 offset:128
	v_mul_f32_e32 v44, v45, v47
	v_cvt_pk_bf16_f32 v44, v44, v44
	v_sad_u32 v45, v123, v119, 0
	v_cvt_f32_u32_e32 v45, v45
	v_cmp_lt_i32_e32 vcc, v123, v119
	ds_write_b16_d16_hi v62, v44 offset:128
	s_nop 0
	v_cndmask_b32_e32 v44, v99, v103, vcc
	v_mul_f32_e32 v44, v44, v45
	v_sub_u32_e32 v45, v122, v119
	v_mul_f32_e32 v44, 0xbfb8aa3b, v44
	v_sub_u32_e32 v46, 0, v45
	v_exp_f32_e32 v44, v44
	v_max_i32_e32 v45, v45, v46
	v_cvt_f32_u32_e32 v45, v45
	v_cmp_lt_i32_e32 vcc, v122, v119
	v_mul_f32_e32 v40, v44, v40
	s_nop 0
	v_cndmask_b32_e32 v44, v99, v103, vcc
	v_mul_f32_e32 v44, v44, v45
	v_mul_f32_e32 v44, 0xbfb8aa3b, v44
	v_exp_f32_e32 v44, v44
	v_bfe_u32 v45, v40, 16, 1
	v_add3_u32 v40, v40, v45, s97
	ds_write_b16_d16_hi v60, v40 offset:160
	v_mul_f32_e32 v40, v44, v41
	v_cvt_pk_bf16_f32 v40, v40, v40
	v_sad_u32 v41, v121, v119, 0
	v_cvt_f32_u32_e32 v41, v41
	v_cmp_lt_i32_e32 vcc, v121, v119
	ds_write_b16_d16_hi v64, v40 offset:160
	s_nop 0
	v_cndmask_b32_e32 v40, v99, v103, vcc
	v_mul_f32_e32 v40, v40, v41
	v_sub_u32_e32 v41, v118, v119
	v_mul_f32_e32 v40, 0xbfb8aa3b, v40
	v_sub_u32_e32 v44, 0, v41
	v_exp_f32_e32 v40, v40
	v_max_i32_e32 v41, v41, v44
	v_cvt_f32_u32_e32 v41, v41
	v_cmp_lt_i32_e32 vcc, v118, v119
	v_mul_f32_e32 v40, v40, v42
	s_nop 0
	v_cndmask_b32_e32 v42, v99, v103, vcc
	v_mul_f32_e32 v41, v42, v41
	v_mul_f32_e32 v41, 0xbfb8aa3b, v41
	v_exp_f32_e32 v41, v41
	v_cvt_pk_bf16_f32 v40, v40, v40
	ds_write_b16_d16_hi v61, v40 offset:160
	v_mul_f32_e32 v40, v41, v43
	v_cvt_pk_bf16_f32 v40, v40, v40
	v_sad_u32 v41, v123, v117, 0
	v_cvt_f32_u32_e32 v41, v41
	v_cmp_lt_i32_e32 vcc, v123, v117
	ds_write_b16_d16_hi v62, v40 offset:160
	s_nop 0
	v_cndmask_b32_e32 v40, v99, v103, vcc
	v_mul_f32_e32 v40, v40, v41
	v_sad_u32 v41, v122, v117, 0
	v_mul_f32_e32 v40, 0xbfb8aa3b, v40
	v_exp_f32_e32 v40, v40
	v_cvt_f32_u32_e32 v41, v41
	v_cmp_lt_i32_e32 vcc, v122, v117
	v_mul_f32_e32 v36, v40, v36
	s_nop 0
	v_cndmask_b32_e32 v40, v99, v103, vcc
	v_mul_f32_e32 v40, v40, v41
	v_mul_f32_e32 v40, 0xbfb8aa3b, v40
	v_exp_f32_e32 v40, v40
	v_cvt_pk_bf16_f32 v36, v36, v36
	ds_write_b16_d16_hi v60, v36 offset:192
	v_mul_f32_e32 v36, v40, v37
	v_cvt_pk_bf16_f32 v36, v36, v36
	v_sad_u32 v37, v121, v117, 0
	v_cvt_f32_u32_e32 v37, v37
	v_cmp_lt_i32_e32 vcc, v121, v117
	ds_write_b16_d16_hi v64, v36 offset:192
	s_nop 0
	v_cndmask_b32_e32 v36, v99, v103, vcc
	v_mul_f32_e32 v36, v36, v37
	v_sad_u32 v37, v118, v117, 0
	v_mul_f32_e32 v36, 0xbfb8aa3b, v36
	v_exp_f32_e32 v36, v36
	v_cvt_f32_u32_e32 v37, v37
	v_cmp_lt_i32_e32 vcc, v118, v117
	v_mul_f32_e32 v36, v36, v38
	v_mad_u64_u32 v[116:117], s[22:23], v105, s4, v[98:99]
	v_cndmask_b32_e32 v38, v99, v103, vcc
	v_mul_f32_e32 v37, v38, v37
	v_mul_f32_e32 v37, 0xbfb8aa3b, v37
	v_exp_f32_e32 v37, v37
	v_cvt_pk_bf16_f32 v36, v36, v36
	ds_write_b16_d16_hi v61, v36 offset:192
	v_mul_f32_e32 v36, v37, v39
	v_cvt_pk_bf16_f32 v36, v36, v36
	v_sad_u32 v37, v123, v115, 0
	v_cvt_f32_u32_e32 v37, v37
	v_cmp_lt_i32_e32 vcc, v123, v115
	ds_write_b16_d16_hi v62, v36 offset:192
	s_nop 0
	v_cndmask_b32_e32 v36, v99, v103, vcc
	v_mul_f32_e32 v36, v36, v37
	v_sub_u32_e32 v37, v122, v115
	v_mul_f32_e32 v36, 0xbfb8aa3b, v36
	v_sub_u32_e32 v38, 0, v37
	v_exp_f32_e32 v36, v36
	v_max_i32_e32 v37, v37, v38
	v_cvt_f32_u32_e32 v37, v37
	v_cmp_lt_i32_e32 vcc, v122, v115
	v_mul_f32_e32 v32, v36, v32
	s_nop 0
	v_cndmask_b32_e32 v36, v99, v103, vcc
	v_mul_f32_e32 v36, v36, v37
	v_mul_f32_e32 v36, 0xbfb8aa3b, v36
	v_exp_f32_e32 v36, v36
	v_bfe_u32 v37, v32, 16, 1
	v_add3_u32 v32, v32, v37, s97
	ds_write_b16_d16_hi v60, v32 offset:224
	v_mul_f32_e32 v32, v36, v33
	v_cvt_pk_bf16_f32 v32, v32, v32
	v_sad_u32 v33, v121, v115, 0
	v_cvt_f32_u32_e32 v33, v33
	v_cmp_lt_i32_e32 vcc, v121, v115
	ds_write_b16_d16_hi v64, v32 offset:224
	s_nop 0
	v_cndmask_b32_e32 v32, v99, v103, vcc
	v_mul_f32_e32 v32, v32, v33
	v_sub_u32_e32 v33, v118, v115
	v_mul_f32_e32 v32, 0xbfb8aa3b, v32
	v_sub_u32_e32 v36, 0, v33
	v_exp_f32_e32 v32, v32
	v_max_i32_e32 v33, v33, v36
	v_cvt_f32_u32_e32 v33, v33
	v_cmp_lt_i32_e32 vcc, v118, v115
	v_mul_f32_e32 v32, v32, v34
	s_nop 0
	v_cndmask_b32_e32 v34, v99, v103, vcc
	v_mul_f32_e32 v33, v34, v33
	v_mul_f32_e32 v33, 0xbfb8aa3b, v33
	v_exp_f32_e32 v33, v33
	v_cvt_pk_bf16_f32 v32, v32, v32
	ds_write_b16_d16_hi v61, v32 offset:224
	v_mul_f32_e32 v32, v33, v35
	v_cvt_pk_bf16_f32 v32, v32, v32
	ds_write_b16_d16_hi v62, v32 offset:224
	s_waitcnt lgkmcnt(0)
	s_barrier
	ds_read_b128 v[32:35], v107 offset:54272
	ds_read_b128 v[48:51], v107 offset:54336
	ds_read_b128 v[40:43], v107 offset:63488
	ds_read_b128 v[52:55], v107 offset:63552
	s_waitcnt lgkmcnt(3)
	v_mfma_f32_16x16x32_bf16 v[36:39], v[24:27], v[32:35], 0
	ds_read_b128 v[72:75], v107 offset:56640
	ds_read_b128 v[76:79], v68 offset:63552
	ds_read_b128 v[84:87], v107 offset:58944
	s_waitcnt lgkmcnt(4)
	v_mfma_f32_16x16x32_bf16 v[44:47], v[24:27], v[40:43], 0
	ds_read_b128 v[128:131], v107 offset:61248
	ds_read_b128 v[148:151], v116 offset:64
	ds_read_b128 v[144:147], v116 offset:4352
	v_mfma_f32_16x16x32_bf16 v[32:35], v[28:31], v[32:35], 0
	ds_read_b128 v[164:167], v116 offset:4544
	v_cmp_lt_i32_e32 vcc, v235, v229
	v_mfma_f32_16x16x32_bf16 v[40:43], v[28:31], v[40:43], 0
	v_mfma_f32_16x16x32_bf16 v[56:59], v[20:23], v[48:51], v[36:39]
	v_mfma_f32_16x16x32_bf16 v[36:39], v[16:19], v[48:51], v[32:35]
	ds_read_b128 v[48:51], v68 offset:63488
	s_waitcnt lgkmcnt(8)
	v_mfma_f32_16x16x32_bf16 v[32:35], v[16:19], v[52:55], v[40:43]
	s_nop 2
	ds_read_b128 v[40:43], v107 offset:56576
	v_mfma_f32_16x16x32_bf16 v[60:63], v[20:23], v[52:55], v[44:47]
	s_waitcnt lgkmcnt(0)
	v_mfma_f32_16x16x32_bf16 v[44:47], v[24:27], v[40:43], 0
	v_mfma_f32_16x16x32_bf16 v[52:55], v[24:27], v[48:51], 0
	v_mfma_f32_16x16x32_bf16 v[40:43], v[28:31], v[40:43], 0
	v_mfma_f32_16x16x32_bf16 v[48:51], v[28:31], v[48:51], 0
	v_mfma_f32_16x16x32_bf16 v[64:67], v[20:23], v[72:75], v[44:47]
	v_mfma_f32_16x16x32_bf16 v[44:47], v[16:19], v[72:75], v[40:43]
	ds_read_b128 v[72:75], v88 offset:63488
	ds_read_b128 v[88:91], v88 offset:63552
	v_mfma_f32_16x16x32_bf16 v[40:43], v[16:19], v[76:79], v[48:51]
	s_nop 2
	ds_read_b128 v[48:51], v107 offset:58880
	v_mfma_f32_16x16x32_bf16 v[68:71], v[20:23], v[76:79], v[52:55]
	s_waitcnt lgkmcnt(0)
	v_mfma_f32_16x16x32_bf16 v[52:55], v[24:27], v[48:51], 0
	v_mfma_f32_16x16x32_bf16 v[48:51], v[28:31], v[48:51], 0
	v_mfma_f32_16x16x32_bf16 v[80:83], v[28:31], v[72:75], 0
	v_mfma_f32_16x16x32_bf16 v[76:79], v[24:27], v[72:75], 0
	v_mfma_f32_16x16x32_bf16 v[72:75], v[20:23], v[84:87], v[52:55]
	v_mfma_f32_16x16x32_bf16 v[52:55], v[16:19], v[84:87], v[48:51]
	v_mfma_f32_16x16x32_bf16 v[48:51], v[16:19], v[88:91], v[80:83]
	s_nop 3
	ds_read_b128 v[80:83], v107 offset:61184
	v_mfma_f32_16x16x32_bf16 v[76:79], v[20:23], v[88:91], v[76:79]
	ds_read_b128 v[88:91], v110 offset:63488
	s_waitcnt lgkmcnt(1)
	v_mfma_f32_16x16x32_bf16 v[84:87], v[24:27], v[80:83], 0
	s_waitcnt lgkmcnt(0)
	v_mfma_f32_16x16x32_bf16 v[92:95], v[24:27], v[88:91], 0
	v_mfma_f32_16x16x32_bf16 v[24:27], v[20:23], v[128:131], v[84:87]
	s_nop 4
	ds_read_b128 v[84:87], v110 offset:63552
	v_mfma_f32_16x16x32_bf16 v[80:83], v[28:31], v[80:83], 0
	v_mfma_f32_16x16x32_bf16 v[88:91], v[28:31], v[88:91], 0
	s_waitcnt lgkmcnt(0)
	v_mfma_f32_16x16x32_bf16 v[28:31], v[20:23], v[84:87], v[92:95]
	v_mfma_f32_16x16x32_bf16 v[20:23], v[16:19], v[128:131], v[80:83]
	s_nop 3
	ds_read_b128 v[80:83], v116
	v_mfma_f32_16x16x32_bf16 v[16:19], v[16:19], v[84:87], v[88:91]
	v_mul_u32_u24_e32 v84, 0x88, v101
	v_lshl_add_u32 v98, v84, 1, v98
	ds_read_b128 v[84:87], v98 offset:36864
	ds_read_b128 v[92:95], v98 offset:41216
	ds_read_b128 v[132:135], v98 offset:45568
	ds_read_b128 v[156:159], v98 offset:45632
	ds_read_b128 v[140:143], v98 offset:49920
	ds_read_b128 v[160:163], v98 offset:49984
	s_waitcnt lgkmcnt(5)
	v_mfma_f32_16x16x32_bf16 v[88:91], v[80:83], v[84:87], 0
	ds_read_b128 v[152:155], v98 offset:41280
	s_waitcnt lgkmcnt(5)
	v_mfma_f32_16x16x32_bf16 v[128:131], v[80:83], v[92:95], 0
	s_waitcnt lgkmcnt(4)
	v_mfma_f32_16x16x32_bf16 v[136:139], v[80:83], v[132:135], 0
	s_waitcnt lgkmcnt(2)
	v_mfma_f32_16x16x32_bf16 v[80:83], v[80:83], v[140:143], 0
	v_mfma_f32_16x16x32_bf16 v[84:87], v[144:147], v[84:87], 0
	v_mfma_f32_16x16x32_bf16 v[92:95], v[144:147], v[92:95], 0
	v_mfma_f32_16x16x32_bf16 v[132:135], v[144:147], v[132:135], 0
	v_mfma_f32_16x16x32_bf16 v[140:143], v[144:147], v[140:143], 0
	ds_read_b128 v[144:147], v98 offset:36928
	s_waitcnt lgkmcnt(0)
	v_mfma_f32_16x16x32_bf16 v[88:91], v[148:151], v[144:147], v[88:91]
	v_mfma_f32_16x16x32_bf16 v[128:131], v[148:151], v[152:155], v[128:131]
	v_mfma_f32_16x16x32_bf16 v[136:139], v[148:151], v[156:159], v[136:139]
	v_mfma_f32_16x16x32_bf16 v[80:83], v[148:151], v[160:163], v[80:83]
	ds_read_b128 v[148:151], v116 offset:4416
	s_waitcnt lgkmcnt(0)
	v_mfma_f32_16x16x32_bf16 v[84:87], v[148:151], v[144:147], v[84:87]
	ds_read_b128 v[144:147], v116 offset:128
	v_mfma_f32_16x16x32_bf16 v[92:95], v[148:151], v[152:155], v[92:95]
	ds_read_b128 v[152:155], v98 offset:41344
	v_mfma_f32_16x16x32_bf16 v[132:135], v[148:151], v[156:159], v[132:135]
	ds_read_b128 v[156:159], v98 offset:45696
	v_mfma_f32_16x16x32_bf16 v[140:143], v[148:151], v[160:163], v[140:143]
	ds_read_b128 v[148:151], v98 offset:36992
	ds_read_b128 v[160:163], v98 offset:50048
	s_waitcnt lgkmcnt(1)
	v_mfma_f32_16x16x32_bf16 v[88:91], v[144:147], v[148:151], v[88:91]
	v_mfma_f32_16x16x32_bf16 v[128:131], v[144:147], v[152:155], v[128:131]
	v_mfma_f32_16x16x32_bf16 v[136:139], v[144:147], v[156:159], v[136:139]
	s_waitcnt lgkmcnt(0)
	v_mfma_f32_16x16x32_bf16 v[80:83], v[144:147], v[160:163], v[80:83]
	ds_read_b128 v[144:147], v116 offset:4480
	s_waitcnt lgkmcnt(0)
	v_mfma_f32_16x16x32_bf16 v[84:87], v[144:147], v[148:151], v[84:87]
	ds_read_b128 v[148:151], v116 offset:192
	v_mfma_f32_16x16x32_bf16 v[92:95], v[144:147], v[152:155], v[92:95]
	v_mfma_f32_16x16x32_bf16 v[132:135], v[144:147], v[156:159], v[132:135]
	ds_read_b128 v[156:159], v98 offset:45760
	v_mfma_f32_16x16x32_bf16 v[140:143], v[144:147], v[160:163], v[140:143]
	ds_read_b128 v[144:147], v98 offset:37056
	ds_read_b128 v[160:163], v98 offset:50112
	s_waitcnt lgkmcnt(1)
	v_mfma_f32_16x16x32_bf16 v[152:155], v[148:151], v[144:147], v[88:91]
	s_nop 2
	ds_read_b128 v[88:91], v98 offset:41408
	s_waitcnt lgkmcnt(0)
	v_mfma_f32_16x16x32_bf16 v[128:131], v[148:151], v[88:91], v[128:131]
	v_mfma_f32_16x16x32_bf16 v[88:91], v[164:167], v[88:91], v[92:95]
	s_nop 2
	v_cvt_f32_i32_e32 v92, v109
	v_sub_u32_e32 v93, 0x80, v100
	v_cvt_f32_i32_e32 v93, v93
	v_mfma_f32_16x16x32_bf16 v[136:139], v[148:151], v[156:159], v[136:139]
	v_mul_f32_e32 v92, v92, v99
	v_mul_f32_e32 v92, 0xbfb8aa3b, v92
	v_exp_f32_e32 v98, v92
	v_mul_f32_e32 v92, v93, v103
	v_mul_f32_e32 v92, 0xbfb8aa3b, v92
	v_exp_f32_e32 v105, v92
	v_fma_f32 v56, v98, v56, v152
	v_fma_f32 v64, v98, v64, v128
	v_mfma_f32_16x16x32_bf16 v[148:151], v[148:151], v[160:163], v[80:83]
	v_fmac_f32_e32 v56, v105, v60
	v_lshlrev_b32_e32 v60, 2, v101
	v_add_u32_e32 v101, v113, v60
	v_fmac_f32_e32 v64, v105, v68
	ds_write2_b32 v101, v56, v64 offset1:16
	v_cvt_f32_i32_e32 v64, v108
	v_sub_u32_e32 v68, 0x80, v109
	v_cvt_f32_i32_e32 v68, v68
	v_fma_f32 v56, v98, v72, v136
	v_mul_f32_e32 v64, v64, v99
	v_mul_f32_e32 v64, 0xbfb8aa3b, v64
	v_mul_f32_e32 v68, v68, v103
	v_exp_f32_e32 v64, v64
	v_mul_f32_e32 v68, 0xbfb8aa3b, v68
	v_exp_f32_e32 v68, v68
	v_fma_f32 v24, v98, v24, v148
	v_fmac_f32_e32 v56, v105, v76
	v_fmac_f32_e32 v24, v105, v28
	ds_write2_b32 v101, v56, v24 offset0:32 offset1:48
	v_fma_f32 v24, v64, v57, v153
	v_fma_f32 v56, v64, v65, v129
	v_fmac_f32_e32 v24, v68, v61
	v_add_u32_e32 v28, v114, v60
	v_fmac_f32_e32 v56, v68, v69
	ds_write2_b32 v28, v24, v56 offset1:16
	v_cvt_f32_i32_e32 v56, v106
	v_sub_u32_e32 v57, 0x80, v108
	v_cvt_f32_i32_e32 v57, v57
	v_fma_f32 v24, v64, v73, v137
	v_mul_f32_e32 v56, v56, v99
	v_mul_f32_e32 v56, 0xbfb8aa3b, v56
	v_mul_f32_e32 v57, v57, v103
	v_exp_f32_e32 v56, v56
	v_mul_f32_e32 v57, 0xbfb8aa3b, v57
	v_exp_f32_e32 v57, v57
	v_fma_f32 v25, v64, v25, v149
	v_fmac_f32_e32 v24, v68, v77
	v_fmac_f32_e32 v25, v68, v29
	ds_write2_b32 v28, v24, v25 offset0:32 offset1:48
	v_fma_f32 v24, v56, v58, v154
	v_fma_f32 v28, v56, v66, v130
	v_fmac_f32_e32 v24, v57, v62
	v_add_u32_e32 v25, v112, v60
	v_fmac_f32_e32 v28, v57, v70
	ds_write2_b32 v25, v24, v28 offset1:16
	v_add_u32_e32 v28, 4, v100
	v_fma_f32 v24, v56, v74, v138
	v_cvt_f32_i32_e32 v28, v28
	v_fma_f32 v26, v56, v26, v150
	v_sub_u32_e32 v29, 0x80, v106
	v_fmac_f32_e32 v24, v57, v78
	v_cvt_f32_i32_e32 v29, v29
	v_fmac_f32_e32 v26, v57, v30
	ds_write2_b32 v25, v24, v26 offset0:32 offset1:48
	v_cvt_f32_i32_e32 v25, v122
	v_sub_u32_e32 v26, 0x80, v123
	v_cvt_f32_i32_e32 v26, v26
	v_mul_f32_e32 v28, v28, v99
	v_mul_f32_e32 v28, 0xbfb8aa3b, v28
	v_mul_f32_e32 v29, v29, v103
	v_exp_f32_e32 v28, v28
	v_mul_f32_e32 v29, 0xbfb8aa3b, v29
	v_mul_f32_e32 v25, v25, v99
	v_exp_f32_e32 v29, v29
	v_mul_f32_e32 v25, 0xbfb8aa3b, v25
	v_mul_f32_e32 v26, v26, v103
	v_mfma_f32_16x16x32_bf16 v[84:87], v[164:167], v[144:147], v[84:87]
	v_exp_f32_e32 v25, v25
	v_mul_f32_e32 v26, 0xbfb8aa3b, v26
	v_exp_f32_e32 v26, v26
	v_mfma_f32_16x16x32_bf16 v[80:83], v[164:167], v[156:159], v[132:135]
	v_fmac_f32_e32 v155, v28, v59
	v_fmac_f32_e32 v131, v28, v67
	v_fmac_f32_e32 v139, v28, v75
	v_mfma_f32_16x16x32_bf16 v[92:95], v[164:167], v[160:163], v[140:143]
	v_fmac_f32_e32 v151, v28, v27
	v_fmac_f32_e32 v155, v29, v63
	v_add_u32_e32 v24, v111, v60
	v_fmac_f32_e32 v131, v29, v71
	v_fmac_f32_e32 v139, v29, v79
	v_fmac_f32_e32 v151, v29, v31
	ds_write2_b32 v24, v155, v131 offset1:16
	ds_write2_b32 v24, v139, v151 offset0:32 offset1:48
	v_fma_f32 v24, v25, v36, v84
	v_fma_f32 v28, v25, v44, v88
	v_fmac_f32_e32 v24, v26, v32
	v_add_u32_e32 v27, v126, v60
	v_fmac_f32_e32 v28, v26, v40
	ds_write2_b32 v27, v24, v28 offset1:16
	v_fma_f32 v24, v25, v52, v80
	v_cvt_f32_i32_e32 v28, v121
	v_fma_f32 v20, v25, v20, v92
	v_sub_u32_e32 v25, 0x80, v122
	v_cvt_f32_i32_e32 v25, v25
	v_mul_f32_e32 v28, v28, v99
	v_mul_f32_e32 v28, 0xbfb8aa3b, v28
	v_exp_f32_e32 v28, v28
	v_mul_f32_e32 v25, v25, v103
	v_mul_f32_e32 v25, 0xbfb8aa3b, v25
	v_exp_f32_e32 v25, v25
	v_fmac_f32_e32 v24, v26, v48
	v_fmac_f32_e32 v20, v26, v16
	ds_write2_b32 v27, v24, v20 offset0:32 offset1:48
	v_fma_f32 v16, v28, v37, v85
	v_fma_f32 v24, v28, v45, v89
	v_fmac_f32_e32 v16, v25, v33
	v_add_u32_e32 v20, v125, v60
	v_fmac_f32_e32 v24, v25, v41
	ds_write2_b32 v20, v16, v24 offset1:16
	v_cvt_f32_i32_e32 v24, v118
	v_sub_u32_e32 v26, 0x80, v121
	v_cvt_f32_i32_e32 v26, v26
	v_fma_f32 v16, v28, v53, v81
	v_mul_f32_e32 v24, v24, v99
	v_mul_f32_e32 v24, 0xbfb8aa3b, v24
	v_mul_f32_e32 v26, v26, v103
	v_exp_f32_e32 v24, v24
	v_mul_f32_e32 v26, 0xbfb8aa3b, v26
	v_exp_f32_e32 v26, v26
	v_fma_f32 v21, v28, v21, v93
	v_fmac_f32_e32 v16, v25, v49
	v_fmac_f32_e32 v21, v25, v17
	ds_write2_b32 v20, v16, v21 offset0:32 offset1:48
	v_fma_f32 v16, v24, v38, v86
	v_fma_f32 v20, v24, v46, v90
	v_fmac_f32_e32 v16, v26, v34
	v_add_u32_e32 v17, v124, v60
	v_fmac_f32_e32 v20, v26, v42
	ds_write2_b32 v17, v16, v20 offset1:16
	v_add_u32_e32 v20, 20, v100
	v_cvt_f32_i32_e32 v20, v20
	v_fma_f32 v21, v24, v22, v94
	v_sub_u32_e32 v22, 0x80, v118
	v_cvt_f32_i32_e32 v22, v22
	v_mul_f32_e32 v20, v20, v99
	v_mul_f32_e32 v20, 0xbfb8aa3b, v20
	v_exp_f32_e32 v20, v20
	v_mul_f32_e32 v22, v22, v103
	v_mul_f32_e32 v22, 0xbfb8aa3b, v22
	v_exp_f32_e32 v22, v22
	v_fma_f32 v16, v24, v54, v82
	v_fmac_f32_e32 v16, v26, v50
	v_fmac_f32_e32 v21, v26, v18
	v_fmac_f32_e32 v87, v20, v39
	v_fmac_f32_e32 v91, v20, v47
	v_fmac_f32_e32 v83, v20, v55
	v_fmac_f32_e32 v95, v20, v23
	ds_write2_b32 v17, v16, v21 offset0:32 offset1:48
	v_fmac_f32_e32 v87, v22, v35
	v_add_u32_e32 v16, v120, v60
	v_fmac_f32_e32 v91, v22, v43
	v_fmac_f32_e32 v83, v22, v51
	v_fmac_f32_e32 v95, v22, v19
	ds_write2_b32 v16, v87, v91 offset1:16
	ds_write2_b32 v16, v83, v95 offset0:32 offset1:48
	v_mul_lo_u32 v16, v102, s4
	v_lshlrev_b32_e32 v17, 2, v104
	v_add3_u32 v44, s2, v16, v17
	s_waitcnt lgkmcnt(0)
	s_barrier
	ds_read_b128 v[36:39], v44
	ds_read_b128 v[32:35], v44 offset:16
	ds_read_b128 v[28:31], v44 offset:32
	ds_read_b128 v[24:27], v44 offset:48
	ds_read_b128 v[20:23], v44 offset:64
	ds_read_b128 v[16:19], v44 offset:80
	s_waitcnt lgkmcnt(5)
	v_add_f32_e32 v40, 0, v36
	v_add_f32_e32 v40, v40, v37
	v_add_f32_e32 v40, v40, v38
	v_add_f32_e32 v40, v40, v39
	s_waitcnt lgkmcnt(4)
	v_add_f32_e32 v40, v40, v32
	v_add_f32_e32 v40, v40, v33
	v_add_f32_e32 v40, v40, v34
	v_add_f32_e32 v40, v40, v35
	s_waitcnt lgkmcnt(3)
	v_add_f32_e32 v40, v40, v28
	v_add_f32_e32 v40, v40, v29
	v_add_f32_e32 v40, v40, v30
	v_add_f32_e32 v40, v40, v31
	s_waitcnt lgkmcnt(2)
	v_add_f32_e32 v40, v40, v24
	v_add_f32_e32 v40, v40, v25
	v_add_f32_e32 v40, v40, v26
	v_add_f32_e32 v40, v40, v27
	s_waitcnt lgkmcnt(1)
	v_add_f32_e32 v40, v40, v20
	v_add_f32_e32 v40, v40, v21
	v_add_f32_e32 v40, v40, v22
	v_add_f32_e32 v40, v40, v23
	s_waitcnt lgkmcnt(0)
	v_add_f32_e32 v40, v40, v16
	v_add_f32_e32 v48, v40, v17
	ds_read_b128 v[40:43], v44 offset:96
	v_cndmask_b32_e32 v45, v228, v235, vcc
	v_add_f32_e32 v48, v48, v18
	v_lshlrev_b32_e32 v49, 2, v45
	ds_read_b128 v[44:47], v44 offset:112
	v_add_f32_e32 v48, v48, v19
	s_waitcnt lgkmcnt(1)
	v_add_f32_e32 v48, v48, v40
	v_add_f32_e32 v48, v48, v41
	v_add_f32_e32 v48, v48, v42
	v_add_f32_e32 v48, v48, v43
	s_waitcnt lgkmcnt(0)
	v_add_f32_e32 v48, v48, v44
	v_add_f32_e32 v48, v48, v45
	v_add_f32_e32 v48, v48, v46
	v_add_f32_e32 v48, v48, v47
	ds_bpermute_b32 v50, v49, v48
	v_readlane_b32 s4, v254, 0
	v_readlane_b32 s5, v254, 1
	s_waitcnt lgkmcnt(0)
	v_add_f32_e32 v50, v48, v50
	v_fmamk_f32 v52, v50, 0xbc800000, v37
	v_fmamk_f32 v51, v50, 0xbc800000, v36
	v_mul_f32_e32 v53, v52, v52
	v_fmac_f32_e32 v53, v51, v51
	v_fmamk_f32 v38, v50, 0xbc800000, v38
	v_fmac_f32_e32 v53, v38, v38
	v_fmac_f32_e32 v39, 0xbc800000, v50
	v_fmac_f32_e32 v53, v39, v39
	v_fmamk_f32 v54, v50, 0xbc800000, v32
	v_fmac_f32_e32 v53, v54, v54
	v_fmamk_f32 v55, v50, 0xbc800000, v33
	v_fmac_f32_e32 v53, v55, v55
	v_fmamk_f32 v34, v50, 0xbc800000, v34
	v_fmac_f32_e32 v53, v34, v34
	v_fmac_f32_e32 v35, 0xbc800000, v50
	v_fmac_f32_e32 v53, v35, v35
	v_fmamk_f32 v56, v50, 0xbc800000, v28
	v_fmac_f32_e32 v53, v56, v56
	v_fmamk_f32 v57, v50, 0xbc800000, v29
	v_fmac_f32_e32 v53, v57, v57
	v_fmamk_f32 v30, v50, 0xbc800000, v30
	v_fmac_f32_e32 v53, v30, v30
	v_fmac_f32_e32 v31, 0xbc800000, v50
	v_fmac_f32_e32 v53, v31, v31
	v_fmamk_f32 v58, v50, 0xbc800000, v24
	v_fmac_f32_e32 v53, v58, v58
	v_fmamk_f32 v59, v50, 0xbc800000, v25
	v_fmac_f32_e32 v53, v59, v59
	v_fmamk_f32 v26, v50, 0xbc800000, v26
	v_fmac_f32_e32 v53, v26, v26
	v_fmac_f32_e32 v27, 0xbc800000, v50
	v_fmac_f32_e32 v53, v27, v27
	v_fmamk_f32 v60, v50, 0xbc800000, v20
	v_fmac_f32_e32 v53, v60, v60
	v_fmamk_f32 v61, v50, 0xbc800000, v21
	v_fmac_f32_e32 v53, v61, v61
	v_fmamk_f32 v22, v50, 0xbc800000, v22
	v_fmac_f32_e32 v53, v22, v22
	v_fmac_f32_e32 v23, 0xbc800000, v50
	v_mul_f32_e32 v48, 0x3c800000, v50
	v_fmac_f32_e32 v53, v23, v23
	v_fmamk_f32 v62, v50, 0xbc800000, v16
	v_fmac_f32_e32 v53, v62, v62
	v_fmac_f32_e32 v17, 0xbc800000, v50
	v_pk_add_f32 v[36:37], v[18:19], v[48:49] op_sel_hi:[1,0] neg_lo:[0,1] neg_hi:[0,1]
	v_fmac_f32_e32 v53, v17, v17
	v_pk_mul_f32 v[18:19], v[36:37], v[36:37]
	v_pk_add_f32 v[32:33], v[40:41], v[48:49] op_sel_hi:[1,0] neg_lo:[0,1] neg_hi:[0,1]
	v_add_f32_e32 v16, v18, v53
	v_add_f32_e32 v16, v19, v16
	v_pk_mul_f32 v[18:19], v[32:33], v[32:33]
	v_pk_add_f32 v[28:29], v[42:43], v[48:49] op_sel_hi:[1,0] neg_lo:[0,1] neg_hi:[0,1]
	v_add_f32_e32 v16, v18, v16
	v_add_f32_e32 v16, v19, v16
	v_pk_mul_f32 v[18:19], v[28:29], v[28:29]
	v_pk_add_f32 v[24:25], v[44:45], v[48:49] op_sel_hi:[1,0] neg_lo:[0,1] neg_hi:[0,1]
	v_add_f32_e32 v16, v18, v16
	v_add_f32_e32 v16, v19, v16
	v_pk_mul_f32 v[18:19], v[24:25], v[24:25]
	s_waitcnt vmcnt(0)
	v_lshlrev_b32_e32 v40, 16, v12
	v_add_f32_e32 v16, v18, v16
	v_add_f32_e32 v16, v19, v16
	v_pk_add_f32 v[18:19], v[46:47], v[48:49] op_sel_hi:[1,0] neg_lo:[0,1] neg_hi:[0,1]
	v_and_b32_e32 v12, 0xffff0000, v12
	v_pk_mul_f32 v[20:21], v[18:19], v[18:19]
	v_mul_f32_e32 v44, 0xbfb8aa3b, v40
	v_add_f32_e32 v16, v20, v16
	v_add_f32_e32 v16, v21, v16
	ds_bpermute_b32 v20, v49, v16
	v_mul_f32_e32 v45, 0xbfb8aa3b, v12
	v_exp_f32_e32 v44, v44
	v_exp_f32_e32 v45, v45
	v_lshlrev_b32_e32 v41, 16, v13
	s_waitcnt lgkmcnt(0)
	v_add_f32_e32 v16, v16, v20
	v_fmamk_f32 v16, v16, 0x3c800000, v219
	v_cmp_gt_f32_e32 vcc, s36, v16
	v_mul_f32_e32 v20, 0x4b800000, v16
	v_add_f32_e32 v44, 1.0, v44
	v_cndmask_b32_e32 v16, v16, v20, vcc
	v_rsq_f32_e32 v16, v16
	v_add_f32_e32 v45, 1.0, v45
	v_rcp_f32_e32 v44, v44
	v_rcp_f32_e32 v45, v45
	v_mul_f32_e32 v20, 0x45800000, v16
	v_cndmask_b32_e32 v16, v16, v20, vcc
	v_and_b32_e32 v13, 0xffff0000, v13
	v_mul_f32_e32 v40, v44, v40
	v_mul_f32_e32 v44, v52, v16
	v_mul_f32_e32 v12, v45, v12
	v_mul_f32_e32 v45, 0xbfb8aa3b, v41
	v_mul_f32_e32 v12, v12, v44
	v_mul_f32_e32 v44, 0xbfb8aa3b, v13
	v_exp_f32_e32 v45, v45
	v_exp_f32_e32 v44, v44
	v_lshlrev_b32_e32 v42, 16, v14
	v_and_b32_e32 v14, 0xffff0000, v14
	v_add_f32_e32 v45, 1.0, v45
	v_add_f32_e32 v44, 1.0, v44
	v_rcp_f32_e32 v45, v45
	v_rcp_f32_e32 v44, v44
	v_mul_f32_e32 v38, v38, v16
	v_mul_f32_e32 v39, v39, v16
	v_mul_f32_e32 v41, v45, v41
	v_mul_f32_e32 v13, v44, v13
	v_mul_f32_e32 v38, v41, v38
	v_mul_f32_e32 v41, 0xbfb8aa3b, v42
	v_mul_f32_e32 v13, v13, v39
	v_mul_f32_e32 v39, 0xbfb8aa3b, v14
	v_exp_f32_e32 v41, v41
	v_exp_f32_e32 v39, v39
	v_lshlrev_b32_e32 v43, 16, v15
	v_and_b32_e32 v15, 0xffff0000, v15
	v_add_f32_e32 v41, 1.0, v41
	v_add_f32_e32 v39, 1.0, v39
	v_rcp_f32_e32 v41, v41
	v_rcp_f32_e32 v39, v39
	v_lshlrev_b64 v[20:21], 11, v[96:97]
	v_lshl_add_u64 v[20:21], s[52:53], 0, v[20:21]
	v_mul_f32_e32 v41, v41, v42
	v_mul_f32_e32 v42, v55, v16
	v_mul_f32_e32 v14, v39, v14
	v_mul_f32_e32 v14, v14, v42
	v_mul_f32_e32 v42, 0xbfb8aa3b, v15
	v_mul_f32_e32 v39, 0xbfb8aa3b, v43
	v_exp_f32_e32 v42, v42
	v_exp_f32_e32 v39, v39
	v_lshl_add_u64 v[20:21], v[20:21], 0, s[88:89]
	v_mul_f32_e32 v46, v51, v16
	v_add_f32_e32 v42, 1.0, v42
	v_add_f32_e32 v39, 1.0, v39
	v_rcp_f32_e32 v42, v42
	v_rcp_f32_e32 v39, v39
	v_mul_f32_e32 v35, v35, v16
	v_lshl_add_u64 v[20:21], v[20:21], 0, v[184:185]
	v_mul_f32_e32 v15, v42, v15
	v_mul_f32_e32 v40, v40, v46
	v_mul_f32_e32 v44, v54, v16
	v_mul_f32_e32 v34, v34, v16
	v_mul_f32_e32 v39, v39, v43
	v_mul_f32_e32 v15, v15, v35
	v_cvt_pk_bf16_f32 v12, v40, v12
	v_mul_f32_e32 v41, v41, v44
	v_mul_f32_e32 v34, v39, v34
	v_cvt_pk_bf16_f32 v13, v38, v13
	v_cvt_pk_bf16_f32 v14, v41, v14
	v_cvt_pk_bf16_f32 v15, v34, v15
	global_store_dwordx4 v[20:21], v[12:15], off
	v_mul_f32_e32 v30, v30, v16
	v_mul_f32_e32 v26, v26, v16
	v_lshlrev_b32_e32 v12, 16, v8
	v_and_b32_e32 v8, 0xffff0000, v8
	v_mul_f32_e32 v34, 0xbfb8aa3b, v12
	v_mul_f32_e32 v35, 0xbfb8aa3b, v8
	v_exp_f32_e32 v34, v34
	v_exp_f32_e32 v35, v35
	v_lshlrev_b32_e32 v13, 16, v9
	v_and_b32_e32 v9, 0xffff0000, v9
	v_add_f32_e32 v34, 1.0, v34
	v_add_f32_e32 v35, 1.0, v35
	v_rcp_f32_e32 v34, v34
	v_rcp_f32_e32 v35, v35
	v_lshlrev_b32_e32 v14, 16, v10
	v_and_b32_e32 v10, 0xffff0000, v10
	v_mul_f32_e32 v12, v34, v12
	v_mul_f32_e32 v34, v57, v16
	v_mul_f32_e32 v8, v35, v8
	v_mul_f32_e32 v35, 0xbfb8aa3b, v13
	v_exp_f32_e32 v35, v35
	v_mul_f32_e32 v8, v8, v34
	v_mul_f32_e32 v34, 0xbfb8aa3b, v9
	v_exp_f32_e32 v34, v34
	v_add_f32_e32 v35, 1.0, v35
	v_rcp_f32_e32 v35, v35
	v_lshlrev_b32_e32 v15, 16, v11
	v_add_f32_e32 v34, 1.0, v34
	v_rcp_f32_e32 v34, v34
	v_mul_f32_e32 v13, v35, v13
	v_mul_f32_e32 v13, v13, v30
	v_mul_f32_e32 v30, v31, v16
	v_mul_f32_e32 v9, v34, v9
	v_mul_f32_e32 v31, 0xbfb8aa3b, v14
	v_mul_f32_e32 v9, v9, v30
	v_mul_f32_e32 v30, 0xbfb8aa3b, v10
	v_exp_f32_e32 v31, v31
	v_exp_f32_e32 v30, v30
	v_and_b32_e32 v11, 0xffff0000, v11
	v_mul_f32_e32 v38, v56, v16
	v_add_f32_e32 v31, 1.0, v31
	v_add_f32_e32 v30, 1.0, v30
	v_rcp_f32_e32 v31, v31
	v_rcp_f32_e32 v30, v30
	v_mul_f32_e32 v12, v12, v38
	v_mul_f32_e32 v34, v58, v16
	v_mul_f32_e32 v14, v31, v14
	v_mul_f32_e32 v31, v59, v16
	v_mul_f32_e32 v10, v30, v10
	v_mul_f32_e32 v30, 0xbfb8aa3b, v15
	v_exp_f32_e32 v30, v30
	v_mul_f32_e32 v10, v10, v31
	v_mul_f32_e32 v31, 0xbfb8aa3b, v11
	v_exp_f32_e32 v31, v31
	v_add_f32_e32 v30, 1.0, v30
	v_rcp_f32_e32 v30, v30
	v_cvt_pk_bf16_f32 v8, v12, v8
	v_add_f32_e32 v31, 1.0, v31
	v_rcp_f32_e32 v31, v31
	v_mul_f32_e32 v15, v30, v15
	v_mul_f32_e32 v15, v15, v26
	v_mul_f32_e32 v26, v27, v16
	v_mul_f32_e32 v11, v31, v11
	v_mul_f32_e32 v11, v11, v26
	v_mul_f32_e32 v14, v14, v34
	v_cvt_pk_bf16_f32 v9, v13, v9
	v_cvt_pk_bf16_f32 v10, v14, v10
	v_cvt_pk_bf16_f32 v11, v15, v11
	global_store_dwordx4 v[20:21], v[8:11], off offset:16
	v_mul_f32_e32 v14, v60, v16
	s_nop 0
	v_lshlrev_b32_e32 v8, 16, v4
	v_and_b32_e32 v4, 0xffff0000, v4
	v_mul_f32_e32 v12, 0xbfb8aa3b, v8
	v_mul_f32_e32 v13, 0xbfb8aa3b, v4
	v_exp_f32_e32 v12, v12
	v_exp_f32_e32 v13, v13
	v_lshlrev_b32_e32 v9, 16, v5
	v_and_b32_e32 v5, 0xffff0000, v5
	v_add_f32_e32 v12, 1.0, v12
	v_add_f32_e32 v13, 1.0, v13
	v_rcp_f32_e32 v12, v12
	v_rcp_f32_e32 v13, v13
	v_lshlrev_b32_e32 v10, 16, v6
	v_and_b32_e32 v6, 0xffff0000, v6
	v_mul_f32_e32 v8, v12, v8
	v_mul_f32_e32 v12, v61, v16
	v_mul_f32_e32 v4, v13, v4
	v_mul_f32_e32 v13, 0xbfb8aa3b, v9
	v_mul_f32_e32 v4, v4, v12
	v_mul_f32_e32 v12, 0xbfb8aa3b, v5
	v_exp_f32_e32 v13, v13
	v_exp_f32_e32 v12, v12
	v_lshlrev_b32_e32 v11, 16, v7
	v_and_b32_e32 v7, 0xffff0000, v7
	v_add_f32_e32 v13, 1.0, v13
	v_add_f32_e32 v12, 1.0, v12
	v_rcp_f32_e32 v13, v13
	v_rcp_f32_e32 v12, v12
	v_mul_f32_e32 v8, v8, v14
	v_mul_f32_e32 v14, v22, v16
	v_mul_f32_e32 v9, v13, v9
	v_mul_f32_e32 v13, v23, v16
	v_mul_f32_e32 v5, v12, v5
	v_mul_f32_e32 v12, 0xbfb8aa3b, v10
	v_mul_f32_e32 v5, v5, v13
	v_mul_f32_e32 v13, 0xbfb8aa3b, v6
	v_exp_f32_e32 v12, v12
	v_exp_f32_e32 v13, v13
	v_mul_f32_e32 v9, v9, v14
	v_mul_f32_e32 v14, v62, v16
	v_add_f32_e32 v12, 1.0, v12
	v_add_f32_e32 v13, 1.0, v13
	v_rcp_f32_e32 v12, v12
	v_rcp_f32_e32 v13, v13
	v_cvt_pk_bf16_f32 v4, v8, v4
	v_cvt_pk_bf16_f32 v5, v9, v5
	v_mul_f32_e32 v10, v12, v10
	v_mul_f32_e32 v12, v17, v16
	v_mul_f32_e32 v6, v13, v6
	v_mul_f32_e32 v13, 0xbfb8aa3b, v11
	v_mul_f32_e32 v6, v6, v12
	v_mul_f32_e32 v12, 0xbfb8aa3b, v7
	v_exp_f32_e32 v13, v13
	v_exp_f32_e32 v12, v12
	v_mul_f32_e32 v10, v10, v14
	v_mul_f32_e32 v14, v36, v16
	v_add_f32_e32 v13, 1.0, v13
	v_add_f32_e32 v12, 1.0, v12
	v_rcp_f32_e32 v13, v13
	v_rcp_f32_e32 v12, v12
	v_cvt_pk_bf16_f32 v6, v10, v6
	v_mul_f32_e32 v10, v32, v16
	v_mul_f32_e32 v11, v13, v11
	v_mul_f32_e32 v13, v37, v16
	v_mul_f32_e32 v7, v12, v7
	v_mul_f32_e32 v7, v7, v13
	v_mul_f32_e32 v11, v11, v14
	v_cvt_pk_bf16_f32 v7, v11, v7
	global_store_dwordx4 v[20:21], v[4:7], off offset:32
	s_nop 1
	v_lshlrev_b32_e32 v4, 16, v0
	v_and_b32_e32 v0, 0xffff0000, v0
	v_mul_f32_e32 v8, 0xbfb8aa3b, v4
	v_mul_f32_e32 v9, 0xbfb8aa3b, v0
	v_exp_f32_e32 v8, v8
	v_exp_f32_e32 v9, v9
	v_lshlrev_b32_e32 v5, 16, v1
	v_and_b32_e32 v1, 0xffff0000, v1
	v_add_f32_e32 v8, 1.0, v8
	v_add_f32_e32 v9, 1.0, v9
	v_rcp_f32_e32 v8, v8
	v_rcp_f32_e32 v9, v9
	v_lshlrev_b32_e32 v6, 16, v2
	v_and_b32_e32 v2, 0xffff0000, v2
	v_mul_f32_e32 v4, v8, v4
	v_mul_f32_e32 v8, v33, v16
	v_mul_f32_e32 v0, v9, v0
	v_mul_f32_e32 v9, 0xbfb8aa3b, v5
	v_mul_f32_e32 v0, v0, v8
	v_mul_f32_e32 v8, 0xbfb8aa3b, v1
	v_exp_f32_e32 v9, v9
	v_exp_f32_e32 v8, v8
	v_lshlrev_b32_e32 v7, 16, v3
	v_and_b32_e32 v3, 0xffff0000, v3
	v_add_f32_e32 v9, 1.0, v9
	v_add_f32_e32 v8, 1.0, v8
	v_rcp_f32_e32 v9, v9
	v_rcp_f32_e32 v8, v8
	v_mul_f32_e32 v4, v4, v10
	v_mul_f32_e32 v10, v28, v16
	v_mul_f32_e32 v5, v9, v5
	v_mul_f32_e32 v9, v29, v16
	v_mul_f32_e32 v1, v8, v1
	v_mul_f32_e32 v8, 0xbfb8aa3b, v6
	v_mul_f32_e32 v1, v1, v9
	v_mul_f32_e32 v9, 0xbfb8aa3b, v2
	v_exp_f32_e32 v8, v8
	v_exp_f32_e32 v9, v9
	v_mul_f32_e32 v5, v5, v10
	v_mul_f32_e32 v10, v24, v16
	v_add_f32_e32 v8, 1.0, v8
	v_add_f32_e32 v9, 1.0, v9
	v_rcp_f32_e32 v8, v8
	v_rcp_f32_e32 v9, v9
	v_cvt_pk_bf16_f32 v0, v4, v0
	v_cvt_pk_bf16_f32 v1, v5, v1
	v_mul_f32_e32 v6, v8, v6
	v_mul_f32_e32 v8, v25, v16
	v_mul_f32_e32 v2, v9, v2
	v_mul_f32_e32 v9, 0xbfb8aa3b, v7
	v_mul_f32_e32 v2, v2, v8
	v_mul_f32_e32 v8, 0xbfb8aa3b, v3
	v_exp_f32_e32 v9, v9
	v_exp_f32_e32 v8, v8
	v_mul_f32_e32 v6, v6, v10
	v_mul_f32_e32 v10, v18, v16
	v_add_f32_e32 v9, 1.0, v9
	v_add_f32_e32 v8, 1.0, v8
	v_rcp_f32_e32 v9, v9
	v_rcp_f32_e32 v8, v8
	v_cvt_pk_bf16_f32 v2, v6, v2
	v_mul_f32_e32 v7, v9, v7
	v_mul_f32_e32 v9, v19, v16
	v_mul_f32_e32 v3, v8, v3
	v_mul_f32_e32 v3, v3, v9
	v_mul_f32_e32 v7, v7, v10
	v_cvt_pk_bf16_f32 v3, v7, v3
	global_store_dwordx4 v[20:21], v[0:3], off offset:48
	s_barrier
	s_load_dword s20, s[4:5], 0x0
	s_waitcnt lgkmcnt(0)
	s_lshl_b32 s20, s20, 1
	s_add_i32 s38, s20, s38
	s_cmp_ge_i32 s38, s30
	s_cbranch_scc1 .LBB0_202
